# GEMM K-loops: per-cluster s_setprio flips replaced by one static s_setprio 1 for waves 4-7 per K-loop
# speedup vs baseline: 1.0081x; 1.0081x over previous
.LBB0_228:
	s_ashr_i32 s25, s24, 31
	s_lshl_b64 s[26:27], s[24:25], 19
	s_add_u32 s26, s48, s26
	s_addc_u32 s27, s49, s27
	s_and_b64 s[28:29], s[6:7], exec
	s_cselect_b32 s1, s27, s9
	s_cselect_b32 s25, s26, s8
	s_ashr_i32 s23, s22, 31
	s_lshl_b64 s[28:29], s[22:23], 19
	s_add_u32 s28, s50, s28
	s_addc_u32 s29, s51, s29
	s_and_b64 s[36:37], s[6:7], exec
	s_cselect_b32 s23, s29, s35
	s_cselect_b32 s38, s28, s34
	s_add_u32 s8, s8, 0x40080
	s_addc_u32 s9, s9, 0
	s_add_u32 s39, s34, 0x100
	v_mov_b32_e32 v4, 0
	s_addc_u32 s40, s35, 0
	s_mov_b32 s41, -2
	v_mov_b32_e32 v5, v4
	v_mov_b32_e32 v6, v4
	v_mov_b32_e32 v7, v4
	v_mov_b32_e32 v8, v4
	v_mov_b32_e32 v9, v4
	v_mov_b32_e32 v10, v4
	v_mov_b32_e32 v11, v4
	v_mov_b32_e32 v20, v4
	v_mov_b32_e32 v21, v4
	v_mov_b32_e32 v22, v4
	v_mov_b32_e32 v23, v4
	v_mov_b32_e32 v24, v4
	v_mov_b32_e32 v25, v4
	v_mov_b32_e32 v26, v4
	v_mov_b32_e32 v27, v4
	v_mov_b32_e32 v52, v4
	v_mov_b32_e32 v53, v4
	v_mov_b32_e32 v54, v4
	v_mov_b32_e32 v55, v4
	v_mov_b32_e32 v56, v4
	v_mov_b32_e32 v57, v4
	v_mov_b32_e32 v58, v4
	v_mov_b32_e32 v59, v4
	v_mov_b32_e32 v68, v4
	v_mov_b32_e32 v69, v4
	v_mov_b32_e32 v70, v4
	v_mov_b32_e32 v71, v4
	v_mov_b32_e32 v72, v4
	v_mov_b32_e32 v73, v4
	v_mov_b32_e32 v74, v4
	v_mov_b32_e32 v75, v4
	v_mov_b32_e32 v12, v4
	v_mov_b32_e32 v13, v4
	v_mov_b32_e32 v14, v4
	v_mov_b32_e32 v15, v4
	v_mov_b32_e32 v16, v4
	v_mov_b32_e32 v17, v4
	v_mov_b32_e32 v18, v4
	v_mov_b32_e32 v19, v4
	v_mov_b32_e32 v28, v4
	v_mov_b32_e32 v29, v4
	v_mov_b32_e32 v30, v4
	v_mov_b32_e32 v31, v4
	v_mov_b32_e32 v48, v4
	v_mov_b32_e32 v49, v4
	v_mov_b32_e32 v50, v4
	v_mov_b32_e32 v51, v4
	v_mov_b32_e32 v60, v4
	v_mov_b32_e32 v61, v4
	v_mov_b32_e32 v62, v4
	v_mov_b32_e32 v63, v4
	v_mov_b32_e32 v64, v4
	v_mov_b32_e32 v65, v4
	v_mov_b32_e32 v66, v4
	v_mov_b32_e32 v67, v4
	v_mov_b32_e32 v76, v4
	v_mov_b32_e32 v77, v4
	v_mov_b32_e32 v78, v4
	v_mov_b32_e32 v79, v4
	v_mov_b32_e32 v80, v4
	v_mov_b32_e32 v81, v4
	v_mov_b32_e32 v82, v4
	v_mov_b32_e32 v83, v4
	v_mov_b32_e32 v84, v4
	v_mov_b32_e32 v85, v4
	v_mov_b32_e32 v86, v4
	v_mov_b32_e32 v87, v4
	v_mov_b32_e32 v88, v4
	v_mov_b32_e32 v89, v4
	v_mov_b32_e32 v90, v4
	v_mov_b32_e32 v91, v4
	v_mov_b32_e32 v100, v4
	v_mov_b32_e32 v101, v4
	v_mov_b32_e32 v102, v4
	v_mov_b32_e32 v103, v4
	v_mov_b32_e32 v104, v4
	v_mov_b32_e32 v105, v4
	v_mov_b32_e32 v106, v4
	v_mov_b32_e32 v107, v4
	v_mov_b32_e32 v116, v4
	v_mov_b32_e32 v117, v4
	v_mov_b32_e32 v118, v4
	v_mov_b32_e32 v119, v4
	v_mov_b32_e32 v120, v4
	v_mov_b32_e32 v121, v4
	v_mov_b32_e32 v122, v4
	v_mov_b32_e32 v123, v4
	v_mov_b32_e32 v132, v4
	v_mov_b32_e32 v133, v4
	v_mov_b32_e32 v134, v4
	v_mov_b32_e32 v135, v4
	v_mov_b32_e32 v136, v4
	v_mov_b32_e32 v137, v4
	v_mov_b32_e32 v138, v4
	v_mov_b32_e32 v139, v4
	v_mov_b32_e32 v92, v4
	v_mov_b32_e32 v93, v4
	v_mov_b32_e32 v94, v4
	v_mov_b32_e32 v95, v4
	v_mov_b32_e32 v96, v4
	v_mov_b32_e32 v97, v4
	v_mov_b32_e32 v98, v4
	v_mov_b32_e32 v99, v4
	v_mov_b32_e32 v108, v4
	v_mov_b32_e32 v109, v4
	v_mov_b32_e32 v110, v4
	v_mov_b32_e32 v111, v4
	v_mov_b32_e32 v112, v4
	v_mov_b32_e32 v113, v4
	v_mov_b32_e32 v114, v4
	v_mov_b32_e32 v115, v4
	v_mov_b32_e32 v124, v4
	v_mov_b32_e32 v125, v4
	v_mov_b32_e32 v126, v4
	v_mov_b32_e32 v127, v4
	v_mov_b32_e32 v128, v4
	v_mov_b32_e32 v129, v4
	v_mov_b32_e32 v130, v4
	v_mov_b32_e32 v131, v4
	v_mov_b32_e32 v140, v4
	v_mov_b32_e32 v141, v4
	v_mov_b32_e32 v142, v4
	v_mov_b32_e32 v143, v4
	v_mov_b32_e32 v144, v4
	v_mov_b32_e32 v145, v4
	v_mov_b32_e32 v146, v4
	v_mov_b32_e32 v147, v4
	s_mov_b64 s[68:69], 0x80
	v_readfirstlane_b32 s100, v0
	s_cmp_lt_u32 s100, 0x100
	s_cbranch_scc1 .Lgprio_6
	s_setprio 1
.Lgprio_6:
.LBB0_229:
	s_add_u32 s34, s8, 0xfffc0080
	s_addc_u32 s35, s9, -1
	s_add_i32 s42, 0, 0x10000
	s_cmp_eq_u32 s41, 12
	s_cselect_b32 s37, s1, s35
	s_cselect_b32 s36, s25, s34
	v_add_u32_e32 v2, s42, v161
	s_cselect_b32 s35, s23, s40
	s_cselect_b32 s34, s38, s39
	s_add_i32 s44, 0, 0x14000
	s_waitcnt vmcnt(0)
	ds_read_b128 v[32:35], v2
	ds_read_b128 v[36:39], v2 offset:1024
	ds_read_b128 v[40:43], v2 offset:2048
	ds_read_b128 v[44:47], v2 offset:3072
	v_add_u32_e32 v2, s44, v161
	ds_read_b128 v[148:151], v2
	ds_read_b128 v[170:173], v2 offset:1024
	ds_read_b128 v[174:177], v2 offset:2048
	ds_read_b128 v[182:185], v2 offset:3072
	v_lshl_add_u64 v[178:179], s[8:9], 0, v[166:167]
	s_add_i32 m0, s31, 0xc000
	ds_read_b128 v[186:189], v181
	ds_read_b128 v[190:193], v181 offset:1024
	ds_read_b128 v[202:205], v181 offset:2048
	ds_read_b128 v[206:209], v181 offset:3072
	ds_read_b128 v[210:213], v181 offset:4096
	ds_read_b128 v[214:217], v181 offset:5120
	ds_read_b128 v[218:221], v181 offset:6144
	ds_read_b128 v[222:225], v181 offset:7168
	global_load_lds_dwordx4 v[178:179], off
	v_lshl_add_u64 v[178:179], s[8:9], 0, v[168:169]
	s_add_i32 m0, s31, 0xe000
	s_nop 0
	global_load_lds_dwordx4 v[178:179], off
	s_waitcnt vmcnt(8)
	s_waitcnt lgkmcnt(0)
	s_barrier
	s_waitcnt lgkmcnt(0)
	v_mfma_f32_16x16x32_bf16 v[144:147], v[32:35], v[186:189], v[144:147]
	v_mfma_f32_16x16x32_bf16 v[140:143], v[40:43], v[186:189], v[140:143]
	v_mfma_f32_16x16x32_bf16 v[128:131], v[32:35], v[202:205], v[128:131]
	v_mfma_f32_16x16x32_bf16 v[124:127], v[40:43], v[202:205], v[124:127]
	v_mfma_f32_16x16x32_bf16 v[112:115], v[32:35], v[210:213], v[112:115]
	v_mfma_f32_16x16x32_bf16 v[108:111], v[40:43], v[210:213], v[108:111]
	v_mfma_f32_16x16x32_bf16 v[96:99], v[32:35], v[218:221], v[96:99]
	v_mfma_f32_16x16x32_bf16 v[92:95], v[40:43], v[218:221], v[92:95]
	v_mfma_f32_16x16x32_bf16 v[144:147], v[36:39], v[190:193], v[144:147]
	v_mfma_f32_16x16x32_bf16 v[140:143], v[44:47], v[190:193], v[140:143]
	v_mfma_f32_16x16x32_bf16 v[128:131], v[36:39], v[206:209], v[128:131]
	v_mfma_f32_16x16x32_bf16 v[124:127], v[44:47], v[206:209], v[124:127]
	v_mfma_f32_16x16x32_bf16 v[112:115], v[36:39], v[214:217], v[112:115]
	v_mfma_f32_16x16x32_bf16 v[108:111], v[44:47], v[214:217], v[108:111]
	v_mfma_f32_16x16x32_bf16 v[96:99], v[36:39], v[222:225], v[96:99]
	v_mfma_f32_16x16x32_bf16 v[92:95], v[44:47], v[222:225], v[92:95]
	v_mfma_f32_16x16x32_bf16 v[136:139], v[148:151], v[186:189], v[136:139]
	v_mfma_f32_16x16x32_bf16 v[132:135], v[174:177], v[186:189], v[132:135]
	v_mfma_f32_16x16x32_bf16 v[120:123], v[148:151], v[202:205], v[120:123]
	v_mfma_f32_16x16x32_bf16 v[116:119], v[174:177], v[202:205], v[116:119]
	v_mfma_f32_16x16x32_bf16 v[104:107], v[148:151], v[210:213], v[104:107]
	v_mfma_f32_16x16x32_bf16 v[100:103], v[174:177], v[210:213], v[100:103]
	v_mfma_f32_16x16x32_bf16 v[88:91], v[148:151], v[218:221], v[88:91]
	v_mfma_f32_16x16x32_bf16 v[84:87], v[174:177], v[218:221], v[84:87]
	v_mfma_f32_16x16x32_bf16 v[136:139], v[170:173], v[190:193], v[136:139]
	v_mfma_f32_16x16x32_bf16 v[132:135], v[182:185], v[190:193], v[132:135]
	v_mfma_f32_16x16x32_bf16 v[120:123], v[170:173], v[206:209], v[120:123]
	v_mfma_f32_16x16x32_bf16 v[116:119], v[182:185], v[206:209], v[116:119]
	v_mfma_f32_16x16x32_bf16 v[104:107], v[170:173], v[214:217], v[104:107]
	v_mfma_f32_16x16x32_bf16 v[100:103], v[182:185], v[214:217], v[100:103]
	v_mfma_f32_16x16x32_bf16 v[88:91], v[170:173], v[222:225], v[88:91]
	v_mfma_f32_16x16x32_bf16 v[84:87], v[182:185], v[222:225], v[84:87]
	s_barrier
	s_add_i32 s42, s42, s52
	v_lshl_add_u64 v[178:179], s[34:35], 0, v[152:153]
	s_mov_b32 m0, s42
	ds_read_b128 v[186:189], v181 offset:16384
	ds_read_b128 v[190:193], v181 offset:17408
	ds_read_b128 v[202:205], v181 offset:18432
	ds_read_b128 v[206:209], v181 offset:19456
	ds_read_b128 v[210:213], v181 offset:20480
	ds_read_b128 v[214:217], v181 offset:21504
	ds_read_b128 v[218:221], v181 offset:22528
	ds_read_b128 v[222:225], v181 offset:23552
	global_load_lds_dwordx4 v[178:179], off
	s_add_i32 m0, s42, 0x2000
	s_add_u32 s42, s34, 0x40000
	v_lshl_add_u64 v[194:195], s[34:35], 0, v[154:155]
	s_addc_u32 s43, s35, 0
	s_add_i32 s44, s44, s52
	global_load_lds_dwordx4 v[194:195], off
	v_lshl_add_u64 v[196:197], s[42:43], 0, v[152:153]
	s_mov_b32 m0, s44
	v_lshl_add_u64 v[198:199], s[36:37], 0, v[154:155]
	global_load_lds_dwordx4 v[196:197], off
	v_lshl_add_u64 v[196:197], s[42:43], 0, v[154:155]
	s_add_i32 m0, s44, 0x2000
	s_nop 0
	global_load_lds_dwordx4 v[196:197], off
	v_lshl_add_u64 v[196:197], s[36:37], 0, v[152:153]
	s_mov_b32 m0, s31
	s_nop 0
	global_load_lds_dwordx4 v[196:197], off
	s_mov_b32 m0, s53
	s_nop 0
	global_load_lds_dwordx4 v[198:199], off
	s_waitcnt vmcnt(8)
	s_waitcnt lgkmcnt(0)
	s_barrier
	s_waitcnt lgkmcnt(0)
	v_mfma_f32_16x16x32_bf16 v[80:83], v[32:35], v[186:189], v[80:83]
	v_mfma_f32_16x16x32_bf16 v[76:79], v[40:43], v[186:189], v[76:79]
	v_mfma_f32_16x16x32_bf16 v[64:67], v[32:35], v[202:205], v[64:67]
	v_mfma_f32_16x16x32_bf16 v[60:63], v[40:43], v[202:205], v[60:63]
	v_mfma_f32_16x16x32_bf16 v[48:51], v[32:35], v[210:213], v[48:51]
	v_mfma_f32_16x16x32_bf16 v[28:31], v[40:43], v[210:213], v[28:31]
	v_mfma_f32_16x16x32_bf16 v[16:19], v[32:35], v[218:221], v[16:19]
	v_mfma_f32_16x16x32_bf16 v[12:15], v[40:43], v[218:221], v[12:15]
	v_mfma_f32_16x16x32_bf16 v[80:83], v[36:39], v[190:193], v[80:83]
	v_mfma_f32_16x16x32_bf16 v[76:79], v[44:47], v[190:193], v[76:79]
	v_mfma_f32_16x16x32_bf16 v[64:67], v[36:39], v[206:209], v[64:67]
	v_mfma_f32_16x16x32_bf16 v[60:63], v[44:47], v[206:209], v[60:63]
	v_mfma_f32_16x16x32_bf16 v[48:51], v[36:39], v[214:217], v[48:51]
	v_mfma_f32_16x16x32_bf16 v[28:31], v[44:47], v[214:217], v[28:31]
	v_mfma_f32_16x16x32_bf16 v[16:19], v[36:39], v[222:225], v[16:19]
	v_mfma_f32_16x16x32_bf16 v[12:15], v[44:47], v[222:225], v[12:15]
	v_mfma_f32_16x16x32_bf16 v[24:27], v[148:151], v[210:213], v[24:27]
	v_mfma_f32_16x16x32_bf16 v[20:23], v[174:177], v[210:213], v[20:23]
	v_mfma_f32_16x16x32_bf16 v[8:11], v[148:151], v[218:221], v[8:11]
	v_mfma_f32_16x16x32_bf16 v[4:7], v[174:177], v[218:221], v[4:7]
	v_mfma_f32_16x16x32_bf16 v[32:35], v[148:151], v[186:189], v[72:75]
	v_mfma_f32_16x16x32_bf16 v[36:39], v[174:177], v[186:189], v[68:71]
	v_mfma_f32_16x16x32_bf16 v[40:43], v[148:151], v[202:205], v[56:59]
	v_mfma_f32_16x16x32_bf16 v[44:47], v[174:177], v[202:205], v[52:55]
	v_mfma_f32_16x16x32_bf16 v[24:27], v[170:173], v[214:217], v[24:27]
	v_mfma_f32_16x16x32_bf16 v[20:23], v[182:185], v[214:217], v[20:23]
	v_mfma_f32_16x16x32_bf16 v[8:11], v[170:173], v[222:225], v[8:11]
	v_mfma_f32_16x16x32_bf16 v[4:7], v[182:185], v[222:225], v[4:7]
	v_mfma_f32_16x16x32_bf16 v[32:35], v[170:173], v[190:193], v[32:35]
	v_mfma_f32_16x16x32_bf16 v[36:39], v[182:185], v[190:193], v[36:39]
	v_mfma_f32_16x16x32_bf16 v[40:43], v[170:173], v[206:209], v[40:43]
	v_mfma_f32_16x16x32_bf16 v[44:47], v[182:185], v[206:209], v[44:47]
	s_barrier
	s_add_i32 s42, 0, 0x18000
	v_add_u32_e32 v2, s42, v161
	s_add_i32 s43, 0, 0x1c000
	ds_read_b128 v[52:55], v2
	ds_read_b128 v[56:59], v2 offset:1024
	ds_read_b128 v[68:71], v2 offset:2048
	ds_read_b128 v[72:75], v2 offset:3072
	v_add_u32_e32 v2, s43, v161
	ds_read_b128 v[148:151], v2
	ds_read_b128 v[170:173], v2 offset:1024
	ds_read_b128 v[174:177], v2 offset:2048
	ds_read_b128 v[182:185], v2 offset:3072
	s_add_u32 s36, s36, 0x40000
	s_addc_u32 s37, s37, 0
	s_mov_b32 m0, s54
	v_lshl_add_u64 v[246:247], s[36:37], 0, v[152:153]
	ds_read_b128 v[186:189], v181 offset:32768
	ds_read_b128 v[190:193], v181 offset:33792
	ds_read_b128 v[202:205], v181 offset:34816
	ds_read_b128 v[206:209], v181 offset:35840
	ds_read_b128 v[210:213], v181 offset:36864
	ds_read_b128 v[214:217], v181 offset:37888
	ds_read_b128 v[218:221], v181 offset:38912
	ds_read_b128 v[222:225], v181 offset:39936
	global_load_lds_dwordx4 v[246:247], off
	v_lshl_add_u64 v[246:247], s[36:37], 0, v[154:155]
	s_mov_b32 m0, s55
	s_nop 0
	global_load_lds_dwordx4 v[246:247], off
	s_waitcnt vmcnt(8)
	s_waitcnt lgkmcnt(0)
	s_barrier
	s_waitcnt lgkmcnt(0)
	v_mfma_f32_16x16x32_bf16 v[144:147], v[52:55], v[186:189], v[144:147]
	v_mfma_f32_16x16x32_bf16 v[140:143], v[68:71], v[186:189], v[140:143]
	v_mfma_f32_16x16x32_bf16 v[128:131], v[52:55], v[202:205], v[128:131]
	v_mfma_f32_16x16x32_bf16 v[124:127], v[68:71], v[202:205], v[124:127]
	v_mfma_f32_16x16x32_bf16 v[112:115], v[52:55], v[210:213], v[112:115]
	v_mfma_f32_16x16x32_bf16 v[108:111], v[68:71], v[210:213], v[108:111]
	v_mfma_f32_16x16x32_bf16 v[96:99], v[52:55], v[218:221], v[96:99]
	v_mfma_f32_16x16x32_bf16 v[92:95], v[68:71], v[218:221], v[92:95]
	v_mfma_f32_16x16x32_bf16 v[144:147], v[56:59], v[190:193], v[144:147]
	v_mfma_f32_16x16x32_bf16 v[140:143], v[72:75], v[190:193], v[140:143]
	v_mfma_f32_16x16x32_bf16 v[128:131], v[56:59], v[206:209], v[128:131]
	v_mfma_f32_16x16x32_bf16 v[124:127], v[72:75], v[206:209], v[124:127]
	v_mfma_f32_16x16x32_bf16 v[112:115], v[56:59], v[214:217], v[112:115]
	v_mfma_f32_16x16x32_bf16 v[108:111], v[72:75], v[214:217], v[108:111]
	v_mfma_f32_16x16x32_bf16 v[96:99], v[56:59], v[222:225], v[96:99]
	v_mfma_f32_16x16x32_bf16 v[92:95], v[72:75], v[222:225], v[92:95]
	v_mfma_f32_16x16x32_bf16 v[136:139], v[148:151], v[186:189], v[136:139]
	v_mfma_f32_16x16x32_bf16 v[132:135], v[174:177], v[186:189], v[132:135]
	v_mfma_f32_16x16x32_bf16 v[120:123], v[148:151], v[202:205], v[120:123]
	v_mfma_f32_16x16x32_bf16 v[116:119], v[174:177], v[202:205], v[116:119]
	v_mfma_f32_16x16x32_bf16 v[104:107], v[148:151], v[210:213], v[104:107]
	v_mfma_f32_16x16x32_bf16 v[100:103], v[174:177], v[210:213], v[100:103]
	v_mfma_f32_16x16x32_bf16 v[88:91], v[148:151], v[218:221], v[88:91]
	v_mfma_f32_16x16x32_bf16 v[84:87], v[174:177], v[218:221], v[84:87]
	v_mfma_f32_16x16x32_bf16 v[136:139], v[170:173], v[190:193], v[136:139]
	v_mfma_f32_16x16x32_bf16 v[132:135], v[182:185], v[190:193], v[132:135]
	v_mfma_f32_16x16x32_bf16 v[120:123], v[170:173], v[206:209], v[120:123]
	v_mfma_f32_16x16x32_bf16 v[116:119], v[182:185], v[206:209], v[116:119]
	v_mfma_f32_16x16x32_bf16 v[104:107], v[170:173], v[214:217], v[104:107]
	v_mfma_f32_16x16x32_bf16 v[100:103], v[182:185], v[214:217], v[100:103]
	v_mfma_f32_16x16x32_bf16 v[88:91], v[170:173], v[222:225], v[88:91]
	v_mfma_f32_16x16x32_bf16 v[84:87], v[182:185], v[222:225], v[84:87]
	s_barrier
	s_add_i32 s36, s42, s52
	v_lshl_add_u64 v[178:179], v[178:179], 0, s[68:69]
	s_mov_b32 m0, s36
	ds_read_b128 v[186:189], v181 offset:49152
	ds_read_b128 v[190:193], v181 offset:50176
	ds_read_b128 v[202:205], v181 offset:51200
	ds_read_b128 v[206:209], v181 offset:52224
	ds_read_b128 v[210:213], v181 offset:53248
	ds_read_b128 v[214:217], v181 offset:54272
	ds_read_b128 v[218:221], v181 offset:55296
	ds_read_b128 v[222:225], v181 offset:56320
	global_load_lds_dwordx4 v[178:179], off
	s_add_i32 m0, s36, 0x2000
	s_add_u32 s34, s34, 0x40080
	v_lshl_add_u64 v[178:179], v[194:195], 0, s[68:69]
	s_addc_u32 s35, s35, 0
	s_add_i32 s36, s43, s52
	global_load_lds_dwordx4 v[178:179], off
	v_lshl_add_u64 v[178:179], s[34:35], 0, v[152:153]
	s_mov_b32 m0, s36
	s_nop 0
	global_load_lds_dwordx4 v[178:179], off
	v_lshl_add_u64 v[178:179], s[34:35], 0, v[154:155]
	s_add_i32 m0, s36, 0x2000
	s_nop 0
	global_load_lds_dwordx4 v[178:179], off
	v_lshl_add_u64 v[178:179], v[196:197], 0, s[68:69]
	s_mov_b32 m0, s57
	s_nop 0
	global_load_lds_dwordx4 v[178:179], off
	v_lshl_add_u64 v[178:179], v[198:199], 0, s[68:69]
	s_mov_b32 m0, s58
	s_nop 0
	global_load_lds_dwordx4 v[178:179], off
	s_waitcnt vmcnt(8)
	s_waitcnt lgkmcnt(0)
	s_barrier
	s_waitcnt lgkmcnt(0)
	v_mfma_f32_16x16x32_bf16 v[80:83], v[52:55], v[186:189], v[80:83]
	v_mfma_f32_16x16x32_bf16 v[76:79], v[68:71], v[186:189], v[76:79]
	v_mfma_f32_16x16x32_bf16 v[64:67], v[52:55], v[202:205], v[64:67]
	v_mfma_f32_16x16x32_bf16 v[60:63], v[68:71], v[202:205], v[60:63]
	v_mfma_f32_16x16x32_bf16 v[48:51], v[52:55], v[210:213], v[48:51]
	v_mfma_f32_16x16x32_bf16 v[28:31], v[68:71], v[210:213], v[28:31]
	v_mfma_f32_16x16x32_bf16 v[16:19], v[52:55], v[218:221], v[16:19]
	v_mfma_f32_16x16x32_bf16 v[12:15], v[68:71], v[218:221], v[12:15]
	v_mfma_f32_16x16x32_bf16 v[80:83], v[56:59], v[190:193], v[80:83]
	v_mfma_f32_16x16x32_bf16 v[76:79], v[72:75], v[190:193], v[76:79]
	v_mfma_f32_16x16x32_bf16 v[64:67], v[56:59], v[206:209], v[64:67]
	v_mfma_f32_16x16x32_bf16 v[60:63], v[72:75], v[206:209], v[60:63]
	v_mfma_f32_16x16x32_bf16 v[48:51], v[56:59], v[214:217], v[48:51]
	v_mfma_f32_16x16x32_bf16 v[28:31], v[72:75], v[214:217], v[28:31]
	v_mfma_f32_16x16x32_bf16 v[16:19], v[56:59], v[222:225], v[16:19]
	v_mfma_f32_16x16x32_bf16 v[12:15], v[72:75], v[222:225], v[12:15]
	v_mfma_f32_16x16x32_bf16 v[32:35], v[148:151], v[186:189], v[32:35]
	v_mfma_f32_16x16x32_bf16 v[72:75], v[170:173], v[190:193], v[32:35]
	v_mfma_f32_16x16x32_bf16 v[32:35], v[174:177], v[186:189], v[36:39]
	v_mfma_f32_16x16x32_bf16 v[68:71], v[182:185], v[190:193], v[32:35]
	v_mfma_f32_16x16x32_bf16 v[32:35], v[148:151], v[202:205], v[40:43]
	v_mfma_f32_16x16x32_bf16 v[56:59], v[170:173], v[206:209], v[32:35]
	v_mfma_f32_16x16x32_bf16 v[32:35], v[174:177], v[202:205], v[44:47]
	v_mfma_f32_16x16x32_bf16 v[24:27], v[148:151], v[210:213], v[24:27]
	v_mfma_f32_16x16x32_bf16 v[20:23], v[174:177], v[210:213], v[20:23]
	v_mfma_f32_16x16x32_bf16 v[8:11], v[148:151], v[218:221], v[8:11]
	v_mfma_f32_16x16x32_bf16 v[4:7], v[174:177], v[218:221], v[4:7]
	v_mfma_f32_16x16x32_bf16 v[52:55], v[182:185], v[206:209], v[32:35]
	v_mfma_f32_16x16x32_bf16 v[24:27], v[170:173], v[214:217], v[24:27]
	v_mfma_f32_16x16x32_bf16 v[20:23], v[182:185], v[214:217], v[20:23]
	v_mfma_f32_16x16x32_bf16 v[8:11], v[170:173], v[222:225], v[8:11]
	v_mfma_f32_16x16x32_bf16 v[4:7], v[182:185], v[222:225], v[4:7]
	s_barrier
	s_add_i32 s41, s41, 2
	s_add_u32 s8, s8, 0x100
	s_addc_u32 s9, s9, 0
	s_add_u32 s39, s39, 0x100
	s_addc_u32 s40, s40, 0
	s_cmp_gt_u32 s41, 13
	s_cbranch_scc0 .LBB0_229
	s_setprio 0
	s_and_b64 vcc, exec, s[20:21]
	s_cbranch_vccz .LBB0_232
	s_barrier

.LBB0_438:
	s_ashr_i32 s19, s18, 31
	s_lshl_b64 s[20:21], s[18:19], 19
	s_add_u32 s20, s37, s20
	s_addc_u32 s21, s38, s21
	s_and_b64 s[22:23], s[6:7], exec
	s_cselect_b32 s19, s21, s29
	s_cselect_b32 s25, s20, s28
	s_ashr_i32 s11, s10, 31
	s_lshl_b64 s[22:23], s[10:11], 19
	s_add_u32 s22, s39, s22
	s_addc_u32 s23, s40, s23
	s_and_b64 s[34:35], s[6:7], exec
	s_cselect_b32 s11, s23, s31
	s_cselect_b32 s27, s22, s30
	s_add_u32 s28, s28, 0x40080
	s_addc_u32 s29, s29, 0
	s_add_u32 s53, s30, 0x100
	v_mov_b32_e32 v4, 0
	s_addc_u32 s54, s31, 0
	s_mov_b32 s55, -2
	v_mov_b32_e32 v5, v4
	v_mov_b32_e32 v6, v4
	v_mov_b32_e32 v7, v4
	v_mov_b32_e32 v8, v4
	v_mov_b32_e32 v9, v4
	v_mov_b32_e32 v10, v4
	v_mov_b32_e32 v11, v4
	v_mov_b32_e32 v36, v4
	v_mov_b32_e32 v37, v4
	v_mov_b32_e32 v38, v4
	v_mov_b32_e32 v39, v4
	v_mov_b32_e32 v40, v4
	v_mov_b32_e32 v41, v4
	v_mov_b32_e32 v42, v4
	v_mov_b32_e32 v43, v4
	v_mov_b32_e32 v52, v4
	v_mov_b32_e32 v53, v4
	v_mov_b32_e32 v54, v4
	v_mov_b32_e32 v55, v4
	v_mov_b32_e32 v56, v4
	v_mov_b32_e32 v57, v4
	v_mov_b32_e32 v58, v4
	v_mov_b32_e32 v59, v4
	v_mov_b32_e32 v68, v4
	v_mov_b32_e32 v69, v4
	v_mov_b32_e32 v70, v4
	v_mov_b32_e32 v71, v4
	v_mov_b32_e32 v72, v4
	v_mov_b32_e32 v73, v4
	v_mov_b32_e32 v74, v4
	v_mov_b32_e32 v75, v4
	v_mov_b32_e32 v12, v4
	v_mov_b32_e32 v13, v4
	v_mov_b32_e32 v14, v4
	v_mov_b32_e32 v15, v4
	v_mov_b32_e32 v16, v4
	v_mov_b32_e32 v17, v4
	v_mov_b32_e32 v18, v4
	v_mov_b32_e32 v19, v4
	v_mov_b32_e32 v44, v4
	v_mov_b32_e32 v45, v4
	v_mov_b32_e32 v46, v4
	v_mov_b32_e32 v47, v4
	v_mov_b32_e32 v48, v4
	v_mov_b32_e32 v49, v4
	v_mov_b32_e32 v50, v4
	v_mov_b32_e32 v51, v4
	v_mov_b32_e32 v60, v4
	v_mov_b32_e32 v61, v4
	v_mov_b32_e32 v62, v4
	v_mov_b32_e32 v63, v4
	v_mov_b32_e32 v64, v4
	v_mov_b32_e32 v65, v4
	v_mov_b32_e32 v66, v4
	v_mov_b32_e32 v67, v4
	v_mov_b32_e32 v76, v4
	v_mov_b32_e32 v77, v4
	v_mov_b32_e32 v78, v4
	v_mov_b32_e32 v79, v4
	v_mov_b32_e32 v80, v4
	v_mov_b32_e32 v81, v4
	v_mov_b32_e32 v82, v4
	v_mov_b32_e32 v83, v4
	v_mov_b32_e32 v84, v4
	v_mov_b32_e32 v85, v4
	v_mov_b32_e32 v86, v4
	v_mov_b32_e32 v87, v4
	v_mov_b32_e32 v88, v4
	v_mov_b32_e32 v89, v4
	v_mov_b32_e32 v90, v4
	v_mov_b32_e32 v91, v4
	v_mov_b32_e32 v100, v4
	v_mov_b32_e32 v101, v4
	v_mov_b32_e32 v102, v4
	v_mov_b32_e32 v103, v4
	v_mov_b32_e32 v104, v4
	v_mov_b32_e32 v105, v4
	v_mov_b32_e32 v106, v4
	v_mov_b32_e32 v107, v4
	v_mov_b32_e32 v116, v4
	v_mov_b32_e32 v117, v4
	v_mov_b32_e32 v118, v4
	v_mov_b32_e32 v119, v4
	v_mov_b32_e32 v120, v4
	v_mov_b32_e32 v121, v4
	v_mov_b32_e32 v122, v4
	v_mov_b32_e32 v123, v4
	v_mov_b32_e32 v132, v4
	v_mov_b32_e32 v133, v4
	v_mov_b32_e32 v134, v4
	v_mov_b32_e32 v135, v4
	v_mov_b32_e32 v136, v4
	v_mov_b32_e32 v137, v4
	v_mov_b32_e32 v138, v4
	v_mov_b32_e32 v139, v4
	v_mov_b32_e32 v92, v4
	v_mov_b32_e32 v93, v4
	v_mov_b32_e32 v94, v4
	v_mov_b32_e32 v95, v4
	v_mov_b32_e32 v96, v4
	v_mov_b32_e32 v97, v4
	v_mov_b32_e32 v98, v4
	v_mov_b32_e32 v99, v4
	v_mov_b32_e32 v108, v4
	v_mov_b32_e32 v109, v4
	v_mov_b32_e32 v110, v4
	v_mov_b32_e32 v111, v4
	v_mov_b32_e32 v112, v4
	v_mov_b32_e32 v113, v4
	v_mov_b32_e32 v114, v4
	v_mov_b32_e32 v115, v4
	v_mov_b32_e32 v124, v4
	v_mov_b32_e32 v125, v4
	v_mov_b32_e32 v126, v4
	v_mov_b32_e32 v127, v4
	v_mov_b32_e32 v128, v4
	v_mov_b32_e32 v129, v4
	v_mov_b32_e32 v130, v4
	v_mov_b32_e32 v131, v4
	v_mov_b32_e32 v140, v4
	v_mov_b32_e32 v141, v4
	v_mov_b32_e32 v142, v4
	v_mov_b32_e32 v143, v4
	v_mov_b32_e32 v144, v4
	v_mov_b32_e32 v145, v4
	v_mov_b32_e32 v146, v4
	v_mov_b32_e32 v147, v4
	s_mov_b64 s[60:61], 0x80
	v_readfirstlane_b32 s100, v0
	s_cmp_lt_u32 s100, 0x100
	s_cbranch_scc1 .Lgprio_5
	s_setprio 1
.Lgprio_5:
.LBB0_439:
	s_add_u32 s30, s28, 0xfffc0080
	s_addc_u32 s31, s29, -1
	s_add_i32 s56, 0, 0x10000
	s_cmp_eq_u32 s55, 12
	s_cselect_b32 s35, s19, s31
	s_cselect_b32 s34, s25, s30
	v_add_u32_e32 v2, s56, v153
	s_cselect_b32 s31, s11, s54
	s_cselect_b32 s30, s27, s53
	s_add_i32 s58, 0, 0x14000
	s_waitcnt vmcnt(0)
	ds_read_b128 v[20:23], v2
	ds_read_b128 v[24:27], v2 offset:1024
	ds_read_b128 v[28:31], v2 offset:2048
	ds_read_b128 v[32:35], v2 offset:3072
	v_add_u32_e32 v2, s58, v153
	ds_read_b128 v[164:167], v2
	ds_read_b128 v[168:171], v2 offset:1024
	ds_read_b128 v[172:175], v2 offset:2048
	ds_read_b128 v[180:183], v2 offset:3072
	v_lshl_add_u64 v[176:177], s[28:29], 0, v[160:161]
	s_add_i32 m0, s42, 0xc000
	ds_read_b128 v[184:187], v178
	ds_read_b128 v[188:191], v178 offset:1024
	ds_read_b128 v[192:195], v178 offset:2048
	ds_read_b128 v[202:205], v178 offset:3072
	ds_read_b128 v[206:209], v178 offset:4096
	ds_read_b128 v[210:213], v178 offset:5120
	ds_read_b128 v[214:217], v178 offset:6144
	ds_read_b128 v[218:221], v178 offset:7168
	global_load_lds_dwordx4 v[176:177], off
	v_lshl_add_u64 v[176:177], s[28:29], 0, v[162:163]
	s_add_i32 m0, s42, 0xe000
	s_nop 0
	global_load_lds_dwordx4 v[176:177], off
	s_waitcnt vmcnt(8)
	s_waitcnt lgkmcnt(0)
	s_barrier
	s_waitcnt lgkmcnt(0)
	v_mfma_f32_16x16x32_bf16 v[144:147], v[20:23], v[184:187], v[144:147]
	v_mfma_f32_16x16x32_bf16 v[140:143], v[28:31], v[184:187], v[140:143]
	v_mfma_f32_16x16x32_bf16 v[128:131], v[20:23], v[192:195], v[128:131]
	v_mfma_f32_16x16x32_bf16 v[124:127], v[28:31], v[192:195], v[124:127]
	v_mfma_f32_16x16x32_bf16 v[112:115], v[20:23], v[206:209], v[112:115]
	v_mfma_f32_16x16x32_bf16 v[108:111], v[28:31], v[206:209], v[108:111]
	v_mfma_f32_16x16x32_bf16 v[96:99], v[20:23], v[214:217], v[96:99]
	v_mfma_f32_16x16x32_bf16 v[92:95], v[28:31], v[214:217], v[92:95]
	v_mfma_f32_16x16x32_bf16 v[144:147], v[24:27], v[188:191], v[144:147]
	v_mfma_f32_16x16x32_bf16 v[140:143], v[32:35], v[188:191], v[140:143]
	v_mfma_f32_16x16x32_bf16 v[128:131], v[24:27], v[202:205], v[128:131]
	v_mfma_f32_16x16x32_bf16 v[124:127], v[32:35], v[202:205], v[124:127]
	v_mfma_f32_16x16x32_bf16 v[112:115], v[24:27], v[210:213], v[112:115]
	v_mfma_f32_16x16x32_bf16 v[108:111], v[32:35], v[210:213], v[108:111]
	v_mfma_f32_16x16x32_bf16 v[96:99], v[24:27], v[218:221], v[96:99]
	v_mfma_f32_16x16x32_bf16 v[92:95], v[32:35], v[218:221], v[92:95]
	v_mfma_f32_16x16x32_bf16 v[136:139], v[164:167], v[184:187], v[136:139]
	v_mfma_f32_16x16x32_bf16 v[132:135], v[172:175], v[184:187], v[132:135]
	v_mfma_f32_16x16x32_bf16 v[120:123], v[164:167], v[192:195], v[120:123]
	v_mfma_f32_16x16x32_bf16 v[116:119], v[172:175], v[192:195], v[116:119]
	v_mfma_f32_16x16x32_bf16 v[104:107], v[164:167], v[206:209], v[104:107]
	v_mfma_f32_16x16x32_bf16 v[100:103], v[172:175], v[206:209], v[100:103]
	v_mfma_f32_16x16x32_bf16 v[88:91], v[164:167], v[214:217], v[88:91]
	v_mfma_f32_16x16x32_bf16 v[84:87], v[172:175], v[214:217], v[84:87]
	v_mfma_f32_16x16x32_bf16 v[136:139], v[168:171], v[188:191], v[136:139]
	v_mfma_f32_16x16x32_bf16 v[132:135], v[180:183], v[188:191], v[132:135]
	v_mfma_f32_16x16x32_bf16 v[120:123], v[168:171], v[202:205], v[120:123]
	v_mfma_f32_16x16x32_bf16 v[116:119], v[180:183], v[202:205], v[116:119]
	v_mfma_f32_16x16x32_bf16 v[104:107], v[168:171], v[210:213], v[104:107]
	v_mfma_f32_16x16x32_bf16 v[100:103], v[180:183], v[210:213], v[100:103]
	v_mfma_f32_16x16x32_bf16 v[88:91], v[168:171], v[218:221], v[88:91]
	v_mfma_f32_16x16x32_bf16 v[84:87], v[180:183], v[218:221], v[84:87]
	s_barrier
	s_add_i32 s56, s56, s41
	v_lshl_add_u64 v[176:177], s[30:31], 0, v[148:149]
	s_mov_b32 m0, s56
	ds_read_b128 v[184:187], v178 offset:16384
	ds_read_b128 v[188:191], v178 offset:17408
	ds_read_b128 v[192:195], v178 offset:18432
	ds_read_b128 v[202:205], v178 offset:19456
	ds_read_b128 v[206:209], v178 offset:20480
	ds_read_b128 v[210:213], v178 offset:21504
	ds_read_b128 v[214:217], v178 offset:22528
	ds_read_b128 v[218:221], v178 offset:23552
	global_load_lds_dwordx4 v[176:177], off
	s_add_i32 m0, s56, 0x2000
	s_add_u32 s56, s30, 0x40000
	v_lshl_add_u64 v[196:197], s[30:31], 0, v[150:151]
	s_addc_u32 s57, s31, 0
	s_add_i32 s58, s58, s41
	global_load_lds_dwordx4 v[196:197], off
	v_lshl_add_u64 v[198:199], s[56:57], 0, v[148:149]
	s_mov_b32 m0, s58
	v_lshl_add_u64 v[222:223], s[34:35], 0, v[150:151]
	global_load_lds_dwordx4 v[198:199], off
	v_lshl_add_u64 v[198:199], s[56:57], 0, v[150:151]
	s_add_i32 m0, s58, 0x2000
	s_nop 0
	global_load_lds_dwordx4 v[198:199], off
	v_lshl_add_u64 v[198:199], s[34:35], 0, v[148:149]
	s_mov_b32 m0, s42
	s_nop 0
	global_load_lds_dwordx4 v[198:199], off
	s_mov_b32 m0, s43
	s_nop 0
	global_load_lds_dwordx4 v[222:223], off
	s_waitcnt vmcnt(8)
	s_waitcnt lgkmcnt(0)
	s_barrier
	s_waitcnt lgkmcnt(0)
	v_mfma_f32_16x16x32_bf16 v[80:83], v[20:23], v[184:187], v[80:83]
	v_mfma_f32_16x16x32_bf16 v[76:79], v[28:31], v[184:187], v[76:79]
	v_mfma_f32_16x16x32_bf16 v[64:67], v[20:23], v[192:195], v[64:67]
	v_mfma_f32_16x16x32_bf16 v[60:63], v[28:31], v[192:195], v[60:63]
	v_mfma_f32_16x16x32_bf16 v[48:51], v[20:23], v[206:209], v[48:51]
	v_mfma_f32_16x16x32_bf16 v[44:47], v[28:31], v[206:209], v[44:47]
	v_mfma_f32_16x16x32_bf16 v[16:19], v[20:23], v[214:217], v[16:19]
	v_mfma_f32_16x16x32_bf16 v[12:15], v[28:31], v[214:217], v[12:15]
	v_mfma_f32_16x16x32_bf16 v[80:83], v[24:27], v[188:191], v[80:83]
	v_mfma_f32_16x16x32_bf16 v[76:79], v[32:35], v[188:191], v[76:79]
	v_mfma_f32_16x16x32_bf16 v[64:67], v[24:27], v[202:205], v[64:67]
	v_mfma_f32_16x16x32_bf16 v[60:63], v[32:35], v[202:205], v[60:63]
	v_mfma_f32_16x16x32_bf16 v[48:51], v[24:27], v[210:213], v[48:51]
	v_mfma_f32_16x16x32_bf16 v[44:47], v[32:35], v[210:213], v[44:47]
	v_mfma_f32_16x16x32_bf16 v[16:19], v[24:27], v[218:221], v[16:19]
	v_mfma_f32_16x16x32_bf16 v[12:15], v[32:35], v[218:221], v[12:15]
	v_mfma_f32_16x16x32_bf16 v[40:43], v[164:167], v[206:209], v[40:43]
	v_mfma_f32_16x16x32_bf16 v[36:39], v[172:175], v[206:209], v[36:39]
	v_mfma_f32_16x16x32_bf16 v[8:11], v[164:167], v[214:217], v[8:11]
	v_mfma_f32_16x16x32_bf16 v[4:7], v[172:175], v[214:217], v[4:7]
	v_mfma_f32_16x16x32_bf16 v[20:23], v[164:167], v[184:187], v[72:75]
	v_mfma_f32_16x16x32_bf16 v[24:27], v[172:175], v[184:187], v[68:71]
	v_mfma_f32_16x16x32_bf16 v[28:31], v[164:167], v[192:195], v[56:59]
	v_mfma_f32_16x16x32_bf16 v[32:35], v[172:175], v[192:195], v[52:55]
	v_mfma_f32_16x16x32_bf16 v[40:43], v[168:171], v[210:213], v[40:43]
	v_mfma_f32_16x16x32_bf16 v[36:39], v[180:183], v[210:213], v[36:39]
	v_mfma_f32_16x16x32_bf16 v[8:11], v[168:171], v[218:221], v[8:11]
	v_mfma_f32_16x16x32_bf16 v[4:7], v[180:183], v[218:221], v[4:7]
	v_mfma_f32_16x16x32_bf16 v[20:23], v[168:171], v[188:191], v[20:23]
	v_mfma_f32_16x16x32_bf16 v[24:27], v[180:183], v[188:191], v[24:27]
	v_mfma_f32_16x16x32_bf16 v[28:31], v[168:171], v[202:205], v[28:31]
	v_mfma_f32_16x16x32_bf16 v[32:35], v[180:183], v[202:205], v[32:35]
	s_barrier
	s_add_i32 s56, 0, 0x18000
	v_add_u32_e32 v2, s56, v153
	s_add_i32 s57, 0, 0x1c000
	ds_read_b128 v[52:55], v2
	ds_read_b128 v[56:59], v2 offset:1024
	ds_read_b128 v[68:71], v2 offset:2048
	ds_read_b128 v[72:75], v2 offset:3072
	v_add_u32_e32 v2, s57, v153
	ds_read_b128 v[164:167], v2
	ds_read_b128 v[168:171], v2 offset:1024
	ds_read_b128 v[172:175], v2 offset:2048
	ds_read_b128 v[180:183], v2 offset:3072
	s_add_u32 s34, s34, 0x40000
	s_addc_u32 s35, s35, 0
	s_mov_b32 m0, s44
	v_lshl_add_u64 v[224:225], s[34:35], 0, v[148:149]
	ds_read_b128 v[184:187], v178 offset:32768
	ds_read_b128 v[188:191], v178 offset:33792
	ds_read_b128 v[192:195], v178 offset:34816
	ds_read_b128 v[202:205], v178 offset:35840
	ds_read_b128 v[206:209], v178 offset:36864
	ds_read_b128 v[210:213], v178 offset:37888
	ds_read_b128 v[214:217], v178 offset:38912
	ds_read_b128 v[218:221], v178 offset:39936
	global_load_lds_dwordx4 v[224:225], off
	v_lshl_add_u64 v[224:225], s[34:35], 0, v[150:151]
	s_mov_b32 m0, s45
	s_nop 0
	global_load_lds_dwordx4 v[224:225], off
	s_waitcnt vmcnt(8)
	s_waitcnt lgkmcnt(0)
	s_barrier
	s_waitcnt lgkmcnt(0)
	v_mfma_f32_16x16x32_bf16 v[144:147], v[52:55], v[184:187], v[144:147]
	v_mfma_f32_16x16x32_bf16 v[140:143], v[68:71], v[184:187], v[140:143]
	v_mfma_f32_16x16x32_bf16 v[128:131], v[52:55], v[192:195], v[128:131]
	v_mfma_f32_16x16x32_bf16 v[124:127], v[68:71], v[192:195], v[124:127]
	v_mfma_f32_16x16x32_bf16 v[112:115], v[52:55], v[206:209], v[112:115]
	v_mfma_f32_16x16x32_bf16 v[108:111], v[68:71], v[206:209], v[108:111]
	v_mfma_f32_16x16x32_bf16 v[96:99], v[52:55], v[214:217], v[96:99]
	v_mfma_f32_16x16x32_bf16 v[92:95], v[68:71], v[214:217], v[92:95]
	v_mfma_f32_16x16x32_bf16 v[144:147], v[56:59], v[188:191], v[144:147]
	v_mfma_f32_16x16x32_bf16 v[140:143], v[72:75], v[188:191], v[140:143]
	v_mfma_f32_16x16x32_bf16 v[128:131], v[56:59], v[202:205], v[128:131]
	v_mfma_f32_16x16x32_bf16 v[124:127], v[72:75], v[202:205], v[124:127]
	v_mfma_f32_16x16x32_bf16 v[112:115], v[56:59], v[210:213], v[112:115]
	v_mfma_f32_16x16x32_bf16 v[108:111], v[72:75], v[210:213], v[108:111]
	v_mfma_f32_16x16x32_bf16 v[96:99], v[56:59], v[218:221], v[96:99]
	v_mfma_f32_16x16x32_bf16 v[92:95], v[72:75], v[218:221], v[92:95]
	v_mfma_f32_16x16x32_bf16 v[136:139], v[164:167], v[184:187], v[136:139]
	v_mfma_f32_16x16x32_bf16 v[132:135], v[172:175], v[184:187], v[132:135]
	v_mfma_f32_16x16x32_bf16 v[120:123], v[164:167], v[192:195], v[120:123]
	v_mfma_f32_16x16x32_bf16 v[116:119], v[172:175], v[192:195], v[116:119]
	v_mfma_f32_16x16x32_bf16 v[104:107], v[164:167], v[206:209], v[104:107]
	v_mfma_f32_16x16x32_bf16 v[100:103], v[172:175], v[206:209], v[100:103]
	v_mfma_f32_16x16x32_bf16 v[88:91], v[164:167], v[214:217], v[88:91]
	v_mfma_f32_16x16x32_bf16 v[84:87], v[172:175], v[214:217], v[84:87]
	v_mfma_f32_16x16x32_bf16 v[136:139], v[168:171], v[188:191], v[136:139]
	v_mfma_f32_16x16x32_bf16 v[132:135], v[180:183], v[188:191], v[132:135]
	v_mfma_f32_16x16x32_bf16 v[120:123], v[168:171], v[202:205], v[120:123]
	v_mfma_f32_16x16x32_bf16 v[116:119], v[180:183], v[202:205], v[116:119]
	v_mfma_f32_16x16x32_bf16 v[104:107], v[168:171], v[210:213], v[104:107]
	v_mfma_f32_16x16x32_bf16 v[100:103], v[180:183], v[210:213], v[100:103]
	v_mfma_f32_16x16x32_bf16 v[88:91], v[168:171], v[218:221], v[88:91]
	v_mfma_f32_16x16x32_bf16 v[84:87], v[180:183], v[218:221], v[84:87]
	s_barrier
	s_add_i32 s34, s56, s41
	v_lshl_add_u64 v[176:177], v[176:177], 0, s[60:61]
	s_mov_b32 m0, s34
	ds_read_b128 v[184:187], v178 offset:49152
	ds_read_b128 v[188:191], v178 offset:50176
	ds_read_b128 v[192:195], v178 offset:51200
	ds_read_b128 v[202:205], v178 offset:52224
	ds_read_b128 v[206:209], v178 offset:53248
	ds_read_b128 v[210:213], v178 offset:54272
	ds_read_b128 v[214:217], v178 offset:55296
	ds_read_b128 v[218:221], v178 offset:56320
	global_load_lds_dwordx4 v[176:177], off
	s_add_i32 m0, s34, 0x2000
	s_add_u32 s30, s30, 0x40080
	v_lshl_add_u64 v[176:177], v[196:197], 0, s[60:61]
	s_addc_u32 s31, s31, 0
	s_add_i32 s34, s57, s41
	global_load_lds_dwordx4 v[176:177], off
	v_lshl_add_u64 v[176:177], s[30:31], 0, v[148:149]
	s_mov_b32 m0, s34
	s_nop 0
	global_load_lds_dwordx4 v[176:177], off
	v_lshl_add_u64 v[176:177], s[30:31], 0, v[150:151]
	s_add_i32 m0, s34, 0x2000
	s_nop 0
	global_load_lds_dwordx4 v[176:177], off
	v_lshl_add_u64 v[176:177], v[198:199], 0, s[60:61]
	s_mov_b32 m0, s47
	s_nop 0
	global_load_lds_dwordx4 v[176:177], off
	v_lshl_add_u64 v[176:177], v[222:223], 0, s[60:61]
	s_mov_b32 m0, s48
	s_nop 0
	global_load_lds_dwordx4 v[176:177], off
	s_waitcnt vmcnt(8)
	s_waitcnt lgkmcnt(0)
	s_barrier
	s_waitcnt lgkmcnt(0)
	v_mfma_f32_16x16x32_bf16 v[80:83], v[52:55], v[184:187], v[80:83]
	v_mfma_f32_16x16x32_bf16 v[76:79], v[68:71], v[184:187], v[76:79]
	v_mfma_f32_16x16x32_bf16 v[64:67], v[52:55], v[192:195], v[64:67]
	v_mfma_f32_16x16x32_bf16 v[60:63], v[68:71], v[192:195], v[60:63]
	v_mfma_f32_16x16x32_bf16 v[48:51], v[52:55], v[206:209], v[48:51]
	v_mfma_f32_16x16x32_bf16 v[44:47], v[68:71], v[206:209], v[44:47]
	v_mfma_f32_16x16x32_bf16 v[16:19], v[52:55], v[214:217], v[16:19]
	v_mfma_f32_16x16x32_bf16 v[12:15], v[68:71], v[214:217], v[12:15]
	v_mfma_f32_16x16x32_bf16 v[80:83], v[56:59], v[188:191], v[80:83]
	v_mfma_f32_16x16x32_bf16 v[76:79], v[72:75], v[188:191], v[76:79]
	v_mfma_f32_16x16x32_bf16 v[64:67], v[56:59], v[202:205], v[64:67]
	v_mfma_f32_16x16x32_bf16 v[60:63], v[72:75], v[202:205], v[60:63]
	v_mfma_f32_16x16x32_bf16 v[48:51], v[56:59], v[210:213], v[48:51]
	v_mfma_f32_16x16x32_bf16 v[44:47], v[72:75], v[210:213], v[44:47]
	v_mfma_f32_16x16x32_bf16 v[16:19], v[56:59], v[218:221], v[16:19]
	v_mfma_f32_16x16x32_bf16 v[12:15], v[72:75], v[218:221], v[12:15]
	v_mfma_f32_16x16x32_bf16 v[20:23], v[164:167], v[184:187], v[20:23]
	v_mfma_f32_16x16x32_bf16 v[72:75], v[168:171], v[188:191], v[20:23]
	v_mfma_f32_16x16x32_bf16 v[20:23], v[172:175], v[184:187], v[24:27]
	v_mfma_f32_16x16x32_bf16 v[68:71], v[180:183], v[188:191], v[20:23]
	v_mfma_f32_16x16x32_bf16 v[20:23], v[164:167], v[192:195], v[28:31]
	v_mfma_f32_16x16x32_bf16 v[56:59], v[168:171], v[202:205], v[20:23]
	v_mfma_f32_16x16x32_bf16 v[20:23], v[172:175], v[192:195], v[32:35]
	v_mfma_f32_16x16x32_bf16 v[52:55], v[180:183], v[202:205], v[20:23]
	v_mfma_f32_16x16x32_bf16 v[20:23], v[164:167], v[206:209], v[40:43]
	v_mfma_f32_16x16x32_bf16 v[40:43], v[168:171], v[210:213], v[20:23]
	v_mfma_f32_16x16x32_bf16 v[20:23], v[172:175], v[206:209], v[36:39]
	v_mfma_f32_16x16x32_bf16 v[8:11], v[164:167], v[214:217], v[8:11]
	v_mfma_f32_16x16x32_bf16 v[4:7], v[172:175], v[214:217], v[4:7]
	v_mfma_f32_16x16x32_bf16 v[36:39], v[180:183], v[210:213], v[20:23]
	v_mfma_f32_16x16x32_bf16 v[8:11], v[168:171], v[218:221], v[8:11]
	v_mfma_f32_16x16x32_bf16 v[4:7], v[180:183], v[218:221], v[4:7]
	s_barrier
	s_add_i32 s55, s55, 2
	s_add_u32 s28, s28, 0x100
	s_addc_u32 s29, s29, 0
	s_add_u32 s53, s53, 0x100
	s_addc_u32 s54, s54, 0
	s_cmp_gt_u32 s55, 13
	s_cbranch_scc0 .LBB0_439
	s_setprio 0
	s_and_b64 vcc, exec, s[12:13]
	s_cbranch_vccz .LBB0_442
	s_barrier

.LBB0_1048:
	s_add_u32 s68, s40, 0x100
	s_addc_u32 s69, s41, 0
	s_ashr_i32 s31, s30, 31
	s_lshl_b64 s[36:37], s[30:31], 19
	s_add_u32 s36, s54, s36
	s_addc_u32 s37, s55, s37
	s_and_b64 s[38:39], s[6:7], exec
	s_cselect_b32 s31, s37, s35
	s_cselect_b32 s70, s36, s34
	s_ashr_i32 s29, s28, 31
	s_lshl_b64 s[38:39], s[28:29], 19
	s_add_u32 s38, s14, s38
	s_addc_u32 s39, s15, s39
	s_and_b64 s[42:43], s[6:7], exec
	s_cselect_b32 s29, s39, s41
	s_cselect_b32 s71, s38, s40
	s_add_u32 s40, s34, 0x40080
	s_addc_u32 s41, s35, 0
	v_lshl_add_u64 v[138:139], s[40:41], 0, v[134:135]
	v_lshl_add_u64 v[140:141], s[40:41], 0, v[136:137]
	s_mov_b32 s72, -2
	s_mov_b64 s[40:41], 0
	s_mov_b64 s[76:77], 0x80
	v_readfirstlane_b32 s100, v0
	s_cmp_lt_u32 s100, 0x100
	s_cbranch_scc1 .Lgprio_4
	s_setprio 1
.Lgprio_4:
.LBB0_1049:
	s_add_u32 s42, s34, s40
	s_addc_u32 s43, s35, s41
	s_add_u32 s42, s42, 0x100
	s_addc_u32 s43, s43, 0
	s_add_u32 s73, s68, s40
	s_addc_u32 s74, s69, s41
	s_add_i32 s75, 0, 0x10000
	s_cmpk_eq_i32 s40, 0x700
	s_cselect_b32 s45, s31, s43
	s_cselect_b32 s44, s70, s42
	s_cselect_b32 s43, s29, s74
	s_cselect_b32 s42, s71, s73
	s_add_i32 s73, 0, 0x14000
	v_add_u32_e32 v156, s75, v142
	v_add_u32_e32 v166, s73, v142
	ds_read_b128 v[144:147], v156
	ds_read_b128 v[148:151], v156 offset:1024
	ds_read_b128 v[152:155], v156 offset:2048
	ds_read_b128 v[156:159], v156 offset:3072
	ds_read_b128 v[160:163], v166
	ds_read_b128 v[170:173], v166 offset:1024
	ds_read_b128 v[174:177], v166 offset:2048
	ds_read_b128 v[178:181], v166 offset:3072
	v_lshl_add_u64 v[166:167], v[138:139], 0, s[40:41]
	s_add_i32 m0, s57, 0xc000
	ds_read_b128 v[182:185], v143
	ds_read_b128 v[186:189], v143 offset:1024
	ds_read_b128 v[190:193], v143 offset:2048
	ds_read_b128 v[194:197], v143 offset:3072
	ds_read_b128 v[202:205], v143 offset:4096
	ds_read_b128 v[206:209], v143 offset:5120
	ds_read_b128 v[210:213], v143 offset:6144
	ds_read_b128 v[214:217], v143 offset:7168
	global_load_lds_dwordx4 v[166:167], off
	v_lshl_add_u64 v[166:167], v[140:141], 0, s[40:41]
	s_add_i32 m0, s57, 0xe000
	s_nop 0
	global_load_lds_dwordx4 v[166:167], off
	s_waitcnt vmcnt(8)
	s_waitcnt lgkmcnt(0)
	s_barrier
	s_waitcnt lgkmcnt(0)
	v_mfma_f32_16x16x32_bf16 v[128:131], v[144:147], v[182:185], v[128:131]
	v_mfma_f32_16x16x32_bf16 v[124:127], v[152:155], v[182:185], v[124:127]
	v_mfma_f32_16x16x32_bf16 v[120:123], v[144:147], v[190:193], v[120:123]
	v_mfma_f32_16x16x32_bf16 v[116:119], v[152:155], v[190:193], v[116:119]
	v_mfma_f32_16x16x32_bf16 v[112:115], v[144:147], v[202:205], v[112:115]
	v_mfma_f32_16x16x32_bf16 v[104:107], v[152:155], v[202:205], v[104:107]
	v_mfma_f32_16x16x32_bf16 v[96:99], v[144:147], v[210:213], v[96:99]
	v_mfma_f32_16x16x32_bf16 v[84:87], v[152:155], v[210:213], v[84:87]
	v_mfma_f32_16x16x32_bf16 v[128:131], v[148:151], v[186:189], v[128:131]
	v_mfma_f32_16x16x32_bf16 v[124:127], v[156:159], v[186:189], v[124:127]
	v_mfma_f32_16x16x32_bf16 v[120:123], v[148:151], v[194:197], v[120:123]
	v_mfma_f32_16x16x32_bf16 v[116:119], v[156:159], v[194:197], v[116:119]
	v_mfma_f32_16x16x32_bf16 v[112:115], v[148:151], v[206:209], v[112:115]
	v_mfma_f32_16x16x32_bf16 v[104:107], v[156:159], v[206:209], v[104:107]
	v_mfma_f32_16x16x32_bf16 v[96:99], v[148:151], v[214:217], v[96:99]
	v_mfma_f32_16x16x32_bf16 v[84:87], v[156:159], v[214:217], v[84:87]
	v_mfma_f32_16x16x32_bf16 v[108:111], v[160:163], v[182:185], v[108:111]
	v_mfma_f32_16x16x32_bf16 v[100:103], v[174:177], v[182:185], v[100:103]
	v_mfma_f32_16x16x32_bf16 v[92:95], v[160:163], v[190:193], v[92:95]
	v_mfma_f32_16x16x32_bf16 v[88:91], v[174:177], v[190:193], v[88:91]
	v_mfma_f32_16x16x32_bf16 v[80:83], v[160:163], v[202:205], v[80:83]
	v_mfma_f32_16x16x32_bf16 v[76:79], v[174:177], v[202:205], v[76:79]
	v_mfma_f32_16x16x32_bf16 v[72:75], v[160:163], v[210:213], v[72:75]
	v_mfma_f32_16x16x32_bf16 v[68:71], v[174:177], v[210:213], v[68:71]
	v_mfma_f32_16x16x32_bf16 v[108:111], v[170:173], v[186:189], v[108:111]
	v_mfma_f32_16x16x32_bf16 v[100:103], v[178:181], v[186:189], v[100:103]
	v_mfma_f32_16x16x32_bf16 v[92:95], v[170:173], v[194:197], v[92:95]
	v_mfma_f32_16x16x32_bf16 v[88:91], v[178:181], v[194:197], v[88:91]
	v_mfma_f32_16x16x32_bf16 v[80:83], v[170:173], v[206:209], v[80:83]
	v_mfma_f32_16x16x32_bf16 v[76:79], v[178:181], v[206:209], v[76:79]
	v_mfma_f32_16x16x32_bf16 v[72:75], v[170:173], v[214:217], v[72:75]
	v_mfma_f32_16x16x32_bf16 v[68:71], v[178:181], v[214:217], v[68:71]
	s_barrier
	s_add_i32 s74, s75, s56
	v_lshl_add_u64 v[166:167], s[42:43], 0, v[2:3]
	s_mov_b32 m0, s74
	ds_read_b128 v[182:185], v143 offset:16384
	ds_read_b128 v[186:189], v143 offset:17408
	ds_read_b128 v[190:193], v143 offset:18432
	ds_read_b128 v[194:197], v143 offset:19456
	ds_read_b128 v[202:205], v143 offset:20480
	ds_read_b128 v[206:209], v143 offset:21504
	ds_read_b128 v[210:213], v143 offset:22528
	ds_read_b128 v[214:217], v143 offset:23552
	global_load_lds_dwordx4 v[166:167], off
	s_add_i32 m0, s74, 0x2000
	s_add_u32 s74, s42, 0x40000
	v_lshl_add_u64 v[198:199], s[42:43], 0, v[132:133]
	s_addc_u32 s75, s43, 0
	s_add_i32 s73, s73, s56
	global_load_lds_dwordx4 v[198:199], off
	v_lshl_add_u64 v[218:219], s[74:75], 0, v[2:3]
	s_mov_b32 m0, s73
	v_lshl_add_u64 v[220:221], s[44:45], 0, v[132:133]
	global_load_lds_dwordx4 v[218:219], off
	v_lshl_add_u64 v[218:219], s[74:75], 0, v[132:133]
	s_add_i32 m0, s73, 0x2000
	s_nop 0
	global_load_lds_dwordx4 v[218:219], off
	v_lshl_add_u64 v[218:219], s[44:45], 0, v[2:3]
	s_mov_b32 m0, s57
	s_nop 0
	global_load_lds_dwordx4 v[218:219], off
	s_mov_b32 m0, s59
	s_nop 0
	global_load_lds_dwordx4 v[220:221], off
	s_waitcnt vmcnt(8)
	s_waitcnt lgkmcnt(0)
	s_barrier
	s_waitcnt lgkmcnt(0)
	v_mfma_f32_16x16x32_bf16 v[64:67], v[144:147], v[182:185], v[64:67]
	v_mfma_f32_16x16x32_bf16 v[60:63], v[152:155], v[182:185], v[60:63]
	v_mfma_f32_16x16x32_bf16 v[56:59], v[144:147], v[190:193], v[56:59]
	v_mfma_f32_16x16x32_bf16 v[52:55], v[152:155], v[190:193], v[52:55]
	v_mfma_f32_16x16x32_bf16 v[32:35], v[144:147], v[202:205], v[32:35]
	v_mfma_f32_16x16x32_bf16 v[28:31], v[152:155], v[202:205], v[28:31]
	v_mfma_f32_16x16x32_bf16 v[24:27], v[144:147], v[210:213], v[24:27]
	v_mfma_f32_16x16x32_bf16 v[20:23], v[152:155], v[210:213], v[20:23]
	v_mfma_f32_16x16x32_bf16 v[64:67], v[148:151], v[186:189], v[64:67]
	v_mfma_f32_16x16x32_bf16 v[60:63], v[156:159], v[186:189], v[60:63]
	v_mfma_f32_16x16x32_bf16 v[56:59], v[148:151], v[194:197], v[56:59]
	v_mfma_f32_16x16x32_bf16 v[52:55], v[156:159], v[194:197], v[52:55]
	v_mfma_f32_16x16x32_bf16 v[32:35], v[148:151], v[206:209], v[32:35]
	v_mfma_f32_16x16x32_bf16 v[28:31], v[156:159], v[206:209], v[28:31]
	v_mfma_f32_16x16x32_bf16 v[24:27], v[148:151], v[214:217], v[24:27]
	v_mfma_f32_16x16x32_bf16 v[20:23], v[156:159], v[214:217], v[20:23]
	v_mfma_f32_16x16x32_bf16 v[48:51], v[160:163], v[182:185], v[48:51]
	v_mfma_f32_16x16x32_bf16 v[44:47], v[174:177], v[182:185], v[44:47]
	v_mfma_f32_16x16x32_bf16 v[40:43], v[160:163], v[190:193], v[40:43]
	v_mfma_f32_16x16x32_bf16 v[36:39], v[174:177], v[190:193], v[36:39]
	v_mfma_f32_16x16x32_bf16 v[16:19], v[160:163], v[202:205], v[16:19]
	v_mfma_f32_16x16x32_bf16 v[12:15], v[174:177], v[202:205], v[12:15]
	v_mfma_f32_16x16x32_bf16 v[8:11], v[160:163], v[210:213], v[8:11]
	v_mfma_f32_16x16x32_bf16 v[4:7], v[174:177], v[210:213], v[4:7]
	v_mfma_f32_16x16x32_bf16 v[48:51], v[170:173], v[186:189], v[48:51]
	v_mfma_f32_16x16x32_bf16 v[44:47], v[178:181], v[186:189], v[44:47]
	v_mfma_f32_16x16x32_bf16 v[40:43], v[170:173], v[194:197], v[40:43]
	v_mfma_f32_16x16x32_bf16 v[36:39], v[178:181], v[194:197], v[36:39]
	v_mfma_f32_16x16x32_bf16 v[16:19], v[170:173], v[206:209], v[16:19]
	v_mfma_f32_16x16x32_bf16 v[12:15], v[178:181], v[206:209], v[12:15]
	v_mfma_f32_16x16x32_bf16 v[8:11], v[170:173], v[214:217], v[8:11]
	v_mfma_f32_16x16x32_bf16 v[4:7], v[178:181], v[214:217], v[4:7]
	s_barrier
	s_add_i32 s73, 0, 0x18000
	s_add_i32 s74, 0, 0x1c000
	v_add_u32_e32 v156, s73, v142
	v_add_u32_e32 v169, s74, v142
	ds_read_b128 v[144:147], v156
	ds_read_b128 v[148:151], v156 offset:1024
	ds_read_b128 v[152:155], v156 offset:2048
	ds_read_b128 v[156:159], v156 offset:3072
	ds_read_b128 v[160:163], v169
	ds_read_b128 v[170:173], v169 offset:1024
	ds_read_b128 v[174:177], v169 offset:2048
	ds_read_b128 v[178:181], v169 offset:3072
	s_add_u32 s44, s44, 0x40000
	s_addc_u32 s45, s45, 0
	s_mov_b32 m0, s60
	v_lshl_add_u64 v[222:223], s[44:45], 0, v[2:3]
	ds_read_b128 v[182:185], v143 offset:32768
	ds_read_b128 v[186:189], v143 offset:33792
	ds_read_b128 v[190:193], v143 offset:34816
	ds_read_b128 v[194:197], v143 offset:35840
	ds_read_b128 v[202:205], v143 offset:36864
	ds_read_b128 v[206:209], v143 offset:37888
	ds_read_b128 v[210:213], v143 offset:38912
	ds_read_b128 v[214:217], v143 offset:39936
	global_load_lds_dwordx4 v[222:223], off
	v_lshl_add_u64 v[222:223], s[44:45], 0, v[132:133]
	s_mov_b32 m0, s61
	s_nop 0
	global_load_lds_dwordx4 v[222:223], off
	s_waitcnt vmcnt(8)
	s_waitcnt lgkmcnt(0)
	s_barrier
	s_waitcnt lgkmcnt(0)
	v_mfma_f32_16x16x32_bf16 v[128:131], v[144:147], v[182:185], v[128:131]
	v_mfma_f32_16x16x32_bf16 v[124:127], v[152:155], v[182:185], v[124:127]
	v_mfma_f32_16x16x32_bf16 v[120:123], v[144:147], v[190:193], v[120:123]
	v_mfma_f32_16x16x32_bf16 v[116:119], v[152:155], v[190:193], v[116:119]
	v_mfma_f32_16x16x32_bf16 v[112:115], v[144:147], v[202:205], v[112:115]
	v_mfma_f32_16x16x32_bf16 v[104:107], v[152:155], v[202:205], v[104:107]
	v_mfma_f32_16x16x32_bf16 v[96:99], v[144:147], v[210:213], v[96:99]
	v_mfma_f32_16x16x32_bf16 v[84:87], v[152:155], v[210:213], v[84:87]
	v_mfma_f32_16x16x32_bf16 v[128:131], v[148:151], v[186:189], v[128:131]
	v_mfma_f32_16x16x32_bf16 v[124:127], v[156:159], v[186:189], v[124:127]
	v_mfma_f32_16x16x32_bf16 v[120:123], v[148:151], v[194:197], v[120:123]
	v_mfma_f32_16x16x32_bf16 v[116:119], v[156:159], v[194:197], v[116:119]
	v_mfma_f32_16x16x32_bf16 v[112:115], v[148:151], v[206:209], v[112:115]
	v_mfma_f32_16x16x32_bf16 v[104:107], v[156:159], v[206:209], v[104:107]
	v_mfma_f32_16x16x32_bf16 v[96:99], v[148:151], v[214:217], v[96:99]
	v_mfma_f32_16x16x32_bf16 v[84:87], v[156:159], v[214:217], v[84:87]
	v_mfma_f32_16x16x32_bf16 v[108:111], v[160:163], v[182:185], v[108:111]
	v_mfma_f32_16x16x32_bf16 v[100:103], v[174:177], v[182:185], v[100:103]
	v_mfma_f32_16x16x32_bf16 v[92:95], v[160:163], v[190:193], v[92:95]
	v_mfma_f32_16x16x32_bf16 v[88:91], v[174:177], v[190:193], v[88:91]
	v_mfma_f32_16x16x32_bf16 v[80:83], v[160:163], v[202:205], v[80:83]
	v_mfma_f32_16x16x32_bf16 v[76:79], v[174:177], v[202:205], v[76:79]
	v_mfma_f32_16x16x32_bf16 v[72:75], v[160:163], v[210:213], v[72:75]
	v_mfma_f32_16x16x32_bf16 v[68:71], v[174:177], v[210:213], v[68:71]
	v_mfma_f32_16x16x32_bf16 v[108:111], v[170:173], v[186:189], v[108:111]
	v_mfma_f32_16x16x32_bf16 v[100:103], v[178:181], v[186:189], v[100:103]
	v_mfma_f32_16x16x32_bf16 v[92:95], v[170:173], v[194:197], v[92:95]
	v_mfma_f32_16x16x32_bf16 v[88:91], v[178:181], v[194:197], v[88:91]
	v_mfma_f32_16x16x32_bf16 v[80:83], v[170:173], v[206:209], v[80:83]
	v_mfma_f32_16x16x32_bf16 v[76:79], v[178:181], v[206:209], v[76:79]
	v_mfma_f32_16x16x32_bf16 v[72:75], v[170:173], v[214:217], v[72:75]
	v_mfma_f32_16x16x32_bf16 v[68:71], v[178:181], v[214:217], v[68:71]
	s_barrier
	s_add_i32 s44, s73, s56
	v_lshl_add_u64 v[166:167], v[166:167], 0, s[76:77]
	s_mov_b32 m0, s44
	ds_read_b128 v[182:185], v143 offset:49152
	ds_read_b128 v[186:189], v143 offset:50176
	ds_read_b128 v[190:193], v143 offset:51200
	ds_read_b128 v[194:197], v143 offset:52224
	ds_read_b128 v[202:205], v143 offset:53248
	ds_read_b128 v[206:209], v143 offset:54272
	ds_read_b128 v[210:213], v143 offset:55296
	ds_read_b128 v[214:217], v143 offset:56320
	global_load_lds_dwordx4 v[166:167], off
	s_add_i32 m0, s44, 0x2000
	s_add_u32 s42, s42, 0x40080
	v_lshl_add_u64 v[166:167], v[198:199], 0, s[76:77]
	s_addc_u32 s43, s43, 0
	s_add_i32 s44, s74, s56
	global_load_lds_dwordx4 v[166:167], off
	v_lshl_add_u64 v[166:167], s[42:43], 0, v[2:3]
	s_mov_b32 m0, s44
	s_nop 0
	global_load_lds_dwordx4 v[166:167], off
	v_lshl_add_u64 v[166:167], s[42:43], 0, v[132:133]
	s_add_i32 m0, s44, 0x2000
	s_nop 0
	global_load_lds_dwordx4 v[166:167], off
	v_lshl_add_u64 v[166:167], v[218:219], 0, s[76:77]
	s_mov_b32 m0, s62
	s_nop 0
	global_load_lds_dwordx4 v[166:167], off
	v_lshl_add_u64 v[166:167], v[220:221], 0, s[76:77]
	s_mov_b32 m0, s63
	s_nop 0
	global_load_lds_dwordx4 v[166:167], off
	s_waitcnt vmcnt(8)
	s_waitcnt lgkmcnt(0)
	s_barrier
	s_waitcnt lgkmcnt(0)
	v_mfma_f32_16x16x32_bf16 v[64:67], v[144:147], v[182:185], v[64:67]
	v_mfma_f32_16x16x32_bf16 v[60:63], v[152:155], v[182:185], v[60:63]
	v_mfma_f32_16x16x32_bf16 v[56:59], v[144:147], v[190:193], v[56:59]
	v_mfma_f32_16x16x32_bf16 v[52:55], v[152:155], v[190:193], v[52:55]
	v_mfma_f32_16x16x32_bf16 v[32:35], v[144:147], v[202:205], v[32:35]
	v_mfma_f32_16x16x32_bf16 v[28:31], v[152:155], v[202:205], v[28:31]
	v_mfma_f32_16x16x32_bf16 v[24:27], v[144:147], v[210:213], v[24:27]
	v_mfma_f32_16x16x32_bf16 v[20:23], v[152:155], v[210:213], v[20:23]
	v_mfma_f32_16x16x32_bf16 v[64:67], v[148:151], v[186:189], v[64:67]
	v_mfma_f32_16x16x32_bf16 v[60:63], v[156:159], v[186:189], v[60:63]
	v_mfma_f32_16x16x32_bf16 v[56:59], v[148:151], v[194:197], v[56:59]
	v_mfma_f32_16x16x32_bf16 v[52:55], v[156:159], v[194:197], v[52:55]
	v_mfma_f32_16x16x32_bf16 v[32:35], v[148:151], v[206:209], v[32:35]
	v_mfma_f32_16x16x32_bf16 v[28:31], v[156:159], v[206:209], v[28:31]
	v_mfma_f32_16x16x32_bf16 v[24:27], v[148:151], v[214:217], v[24:27]
	v_mfma_f32_16x16x32_bf16 v[20:23], v[156:159], v[214:217], v[20:23]
	v_mfma_f32_16x16x32_bf16 v[48:51], v[160:163], v[182:185], v[48:51]
	v_mfma_f32_16x16x32_bf16 v[44:47], v[174:177], v[182:185], v[44:47]
	v_mfma_f32_16x16x32_bf16 v[40:43], v[160:163], v[190:193], v[40:43]
	v_mfma_f32_16x16x32_bf16 v[36:39], v[174:177], v[190:193], v[36:39]
	v_mfma_f32_16x16x32_bf16 v[16:19], v[160:163], v[202:205], v[16:19]
	v_mfma_f32_16x16x32_bf16 v[12:15], v[174:177], v[202:205], v[12:15]
	v_mfma_f32_16x16x32_bf16 v[8:11], v[160:163], v[210:213], v[8:11]
	v_mfma_f32_16x16x32_bf16 v[4:7], v[174:177], v[210:213], v[4:7]
	v_mfma_f32_16x16x32_bf16 v[48:51], v[170:173], v[186:189], v[48:51]
	v_mfma_f32_16x16x32_bf16 v[44:47], v[178:181], v[186:189], v[44:47]
	v_mfma_f32_16x16x32_bf16 v[40:43], v[170:173], v[194:197], v[40:43]
	v_mfma_f32_16x16x32_bf16 v[36:39], v[178:181], v[194:197], v[36:39]
	v_mfma_f32_16x16x32_bf16 v[16:19], v[170:173], v[206:209], v[16:19]
	v_mfma_f32_16x16x32_bf16 v[12:15], v[178:181], v[206:209], v[12:15]
	v_mfma_f32_16x16x32_bf16 v[8:11], v[170:173], v[214:217], v[8:11]
	v_mfma_f32_16x16x32_bf16 v[4:7], v[178:181], v[214:217], v[4:7]
	s_barrier
	s_add_i32 s72, s72, 2
	s_add_u32 s40, s40, 0x100
	s_addc_u32 s41, s41, 0
	s_cmp_gt_u32 s72, 13
	s_cbranch_scc0 .LBB0_1049
	s_setprio 0
	s_and_b64 vcc, exec, s[26:27]
	s_cbranch_vccz .LBB0_1052
	s_barrier

.LBB0_1574:
	s_waitcnt lgkmcnt(0)
	s_ashr_i32 s19, s18, 31
	s_lshl_b64 s[20:21], s[18:19], 19
	s_add_u32 s20, s44, s20
	s_addc_u32 s21, s45, s21
	s_and_b64 s[22:23], s[4:5], exec
	s_cselect_b32 s19, s21, s27
	s_cselect_b32 s55, s20, s26
	s_ashr_i32 s17, s16, 31
	s_lshl_b64 s[22:23], s[16:17], 19
	s_add_u32 s22, s36, s22
	s_addc_u32 s23, s37, s23
	s_and_b64 s[30:31], s[4:5], exec
	s_cselect_b32 s17, s23, s29
	s_cselect_b32 s56, s22, s28
	s_add_u32 s26, s26, 0x40080
	s_addc_u32 s27, s27, 0
	s_add_u32 s57, s28, 0x100
	v_mov_b32_e32 v4, 0
	s_addc_u32 s58, s29, 0
	s_mov_b32 s59, -2
	v_mov_b32_e32 v5, v4
	v_mov_b32_e32 v6, v4
	v_mov_b32_e32 v7, v4
	v_mov_b32_e32 v12, v4
	v_mov_b32_e32 v13, v4
	v_mov_b32_e32 v14, v4
	v_mov_b32_e32 v15, v4
	v_mov_b32_e32 v20, v4
	v_mov_b32_e32 v21, v4
	v_mov_b32_e32 v22, v4
	v_mov_b32_e32 v23, v4
	v_mov_b32_e32 v28, v4
	v_mov_b32_e32 v29, v4
	v_mov_b32_e32 v30, v4
	v_mov_b32_e32 v31, v4
	v_mov_b32_e32 v36, v4
	v_mov_b32_e32 v37, v4
	v_mov_b32_e32 v38, v4
	v_mov_b32_e32 v39, v4
	v_mov_b32_e32 v44, v4
	v_mov_b32_e32 v45, v4
	v_mov_b32_e32 v46, v4
	v_mov_b32_e32 v47, v4
	v_mov_b32_e32 v52, v4
	v_mov_b32_e32 v53, v4
	v_mov_b32_e32 v54, v4
	v_mov_b32_e32 v55, v4
	v_mov_b32_e32 v60, v4
	v_mov_b32_e32 v61, v4
	v_mov_b32_e32 v62, v4
	v_mov_b32_e32 v63, v4
	v_mov_b32_e32 v8, v4
	v_mov_b32_e32 v9, v4
	v_mov_b32_e32 v10, v4
	v_mov_b32_e32 v11, v4
	v_mov_b32_e32 v16, v4
	v_mov_b32_e32 v17, v4
	v_mov_b32_e32 v18, v4
	v_mov_b32_e32 v19, v4
	v_mov_b32_e32 v24, v4
	v_mov_b32_e32 v25, v4
	v_mov_b32_e32 v26, v4
	v_mov_b32_e32 v27, v4
	v_mov_b32_e32 v32, v4
	v_mov_b32_e32 v33, v4
	v_mov_b32_e32 v34, v4
	v_mov_b32_e32 v35, v4
	v_mov_b32_e32 v40, v4
	v_mov_b32_e32 v41, v4
	v_mov_b32_e32 v42, v4
	v_mov_b32_e32 v43, v4
	v_mov_b32_e32 v48, v4
	v_mov_b32_e32 v49, v4
	v_mov_b32_e32 v50, v4
	v_mov_b32_e32 v51, v4
	v_mov_b32_e32 v56, v4
	v_mov_b32_e32 v57, v4
	v_mov_b32_e32 v58, v4
	v_mov_b32_e32 v59, v4
	v_mov_b32_e32 v64, v4
	v_mov_b32_e32 v65, v4
	v_mov_b32_e32 v66, v4
	v_mov_b32_e32 v67, v4
	v_mov_b32_e32 v68, v4
	v_mov_b32_e32 v69, v4
	v_mov_b32_e32 v70, v4
	v_mov_b32_e32 v71, v4
	v_mov_b32_e32 v76, v4
	v_mov_b32_e32 v77, v4
	v_mov_b32_e32 v78, v4
	v_mov_b32_e32 v79, v4
	v_mov_b32_e32 v84, v4
	v_mov_b32_e32 v85, v4
	v_mov_b32_e32 v86, v4
	v_mov_b32_e32 v87, v4
	v_mov_b32_e32 v92, v4
	v_mov_b32_e32 v93, v4
	v_mov_b32_e32 v94, v4
	v_mov_b32_e32 v95, v4
	v_mov_b32_e32 v100, v4
	v_mov_b32_e32 v101, v4
	v_mov_b32_e32 v102, v4
	v_mov_b32_e32 v103, v4
	v_mov_b32_e32 v108, v4
	v_mov_b32_e32 v109, v4
	v_mov_b32_e32 v110, v4
	v_mov_b32_e32 v111, v4
	v_mov_b32_e32 v116, v4
	v_mov_b32_e32 v117, v4
	v_mov_b32_e32 v118, v4
	v_mov_b32_e32 v119, v4
	v_mov_b32_e32 v124, v4
	v_mov_b32_e32 v125, v4
	v_mov_b32_e32 v126, v4
	v_mov_b32_e32 v127, v4
	v_mov_b32_e32 v72, v4
	v_mov_b32_e32 v73, v4
	v_mov_b32_e32 v74, v4
	v_mov_b32_e32 v75, v4
	v_mov_b32_e32 v80, v4
	v_mov_b32_e32 v81, v4
	v_mov_b32_e32 v82, v4
	v_mov_b32_e32 v83, v4
	v_mov_b32_e32 v88, v4
	v_mov_b32_e32 v89, v4
	v_mov_b32_e32 v90, v4
	v_mov_b32_e32 v91, v4
	v_mov_b32_e32 v96, v4
	v_mov_b32_e32 v97, v4
	v_mov_b32_e32 v98, v4
	v_mov_b32_e32 v99, v4
	v_mov_b32_e32 v104, v4
	v_mov_b32_e32 v105, v4
	v_mov_b32_e32 v106, v4
	v_mov_b32_e32 v107, v4
	v_mov_b32_e32 v112, v4
	v_mov_b32_e32 v113, v4
	v_mov_b32_e32 v114, v4
	v_mov_b32_e32 v115, v4
	v_mov_b32_e32 v120, v4
	v_mov_b32_e32 v121, v4
	v_mov_b32_e32 v122, v4
	v_mov_b32_e32 v123, v4
	v_mov_b32_e32 v128, v4
	v_mov_b32_e32 v129, v4
	v_mov_b32_e32 v130, v4
	v_mov_b32_e32 v131, v4
	s_mov_b64 s[66:67], 0x80
	v_readfirstlane_b32 s100, v0
	s_cmp_lt_u32 s100, 0x100
	s_cbranch_scc1 .Lgprio_3
	s_setprio 1
.Lgprio_3:
.LBB0_1575:
	s_add_u32 s28, s26, 0xfffc0080
	s_addc_u32 s29, s27, -1
	s_add_i32 s60, 0, 0x10000
	s_cmp_eq_u32 s59, 12
	s_cselect_b32 s31, s19, s29
	s_cselect_b32 s30, s55, s28
	s_cselect_b32 s29, s17, s58
	s_cselect_b32 s28, s56, s57
	s_add_i32 s62, 0, 0x14000
	v_add_u32_e32 v158, s60, v147
	v_add_u32_e32 v174, s62, v147
	ds_read_b128 v[142:145], v158
	ds_read_b128 v[150:153], v158 offset:1024
	ds_read_b128 v[154:157], v158 offset:2048
	ds_read_b128 v[158:161], v158 offset:3072
	ds_read_b128 v[162:165], v174
	ds_read_b128 v[166:169], v174 offset:1024
	ds_read_b128 v[170:173], v174 offset:2048
	ds_read_b128 v[174:177], v174 offset:3072
	v_lshl_add_u64 v[198:199], s[26:27], 0, v[138:139]
	s_add_i32 m0, s47, 0xc000
	ds_read_b128 v[178:181], v149
	ds_read_b128 v[182:185], v149 offset:1024
	ds_read_b128 v[186:189], v149 offset:2048
	ds_read_b128 v[190:193], v149 offset:3072
	ds_read_b128 v[194:197], v149 offset:4096
	ds_read_b128 v[202:205], v149 offset:5120
	ds_read_b128 v[206:209], v149 offset:6144
	ds_read_b128 v[210:213], v149 offset:7168
	global_load_lds_dwordx4 v[198:199], off
	v_lshl_add_u64 v[198:199], s[26:27], 0, v[140:141]
	s_add_i32 m0, s47, 0xe000
	s_nop 0
	global_load_lds_dwordx4 v[198:199], off
	s_waitcnt vmcnt(8)
	s_waitcnt lgkmcnt(0)
	s_barrier
	s_waitcnt lgkmcnt(0)
	v_mfma_f32_16x16x32_bf16 v[128:131], v[142:145], v[178:181], v[128:131]
	v_mfma_f32_16x16x32_bf16 v[120:123], v[154:157], v[178:181], v[120:123]
	v_mfma_f32_16x16x32_bf16 v[112:115], v[142:145], v[186:189], v[112:115]
	v_mfma_f32_16x16x32_bf16 v[104:107], v[154:157], v[186:189], v[104:107]
	v_mfma_f32_16x16x32_bf16 v[96:99], v[142:145], v[194:197], v[96:99]
	v_mfma_f32_16x16x32_bf16 v[88:91], v[154:157], v[194:197], v[88:91]
	v_mfma_f32_16x16x32_bf16 v[80:83], v[142:145], v[206:209], v[80:83]
	v_mfma_f32_16x16x32_bf16 v[72:75], v[154:157], v[206:209], v[72:75]
	v_mfma_f32_16x16x32_bf16 v[128:131], v[150:153], v[182:185], v[128:131]
	v_mfma_f32_16x16x32_bf16 v[120:123], v[158:161], v[182:185], v[120:123]
	v_mfma_f32_16x16x32_bf16 v[112:115], v[150:153], v[190:193], v[112:115]
	v_mfma_f32_16x16x32_bf16 v[104:107], v[158:161], v[190:193], v[104:107]
	v_mfma_f32_16x16x32_bf16 v[96:99], v[150:153], v[202:205], v[96:99]
	v_mfma_f32_16x16x32_bf16 v[88:91], v[158:161], v[202:205], v[88:91]
	v_mfma_f32_16x16x32_bf16 v[80:83], v[150:153], v[210:213], v[80:83]
	v_mfma_f32_16x16x32_bf16 v[72:75], v[158:161], v[210:213], v[72:75]
	v_mfma_f32_16x16x32_bf16 v[124:127], v[162:165], v[178:181], v[124:127]
	v_mfma_f32_16x16x32_bf16 v[116:119], v[170:173], v[178:181], v[116:119]
	v_mfma_f32_16x16x32_bf16 v[108:111], v[162:165], v[186:189], v[108:111]
	v_mfma_f32_16x16x32_bf16 v[100:103], v[170:173], v[186:189], v[100:103]
	v_mfma_f32_16x16x32_bf16 v[92:95], v[162:165], v[194:197], v[92:95]
	v_mfma_f32_16x16x32_bf16 v[84:87], v[170:173], v[194:197], v[84:87]
	v_mfma_f32_16x16x32_bf16 v[76:79], v[162:165], v[206:209], v[76:79]
	v_mfma_f32_16x16x32_bf16 v[68:71], v[170:173], v[206:209], v[68:71]
	v_mfma_f32_16x16x32_bf16 v[124:127], v[166:169], v[182:185], v[124:127]
	v_mfma_f32_16x16x32_bf16 v[116:119], v[174:177], v[182:185], v[116:119]
	v_mfma_f32_16x16x32_bf16 v[108:111], v[166:169], v[190:193], v[108:111]
	v_mfma_f32_16x16x32_bf16 v[100:103], v[174:177], v[190:193], v[100:103]
	v_mfma_f32_16x16x32_bf16 v[92:95], v[166:169], v[202:205], v[92:95]
	v_mfma_f32_16x16x32_bf16 v[84:87], v[174:177], v[202:205], v[84:87]
	v_mfma_f32_16x16x32_bf16 v[76:79], v[166:169], v[210:213], v[76:79]
	v_mfma_f32_16x16x32_bf16 v[68:71], v[174:177], v[210:213], v[68:71]
	s_barrier
	s_add_i32 s60, s60, s46
	v_lshl_add_u64 v[198:199], s[28:29], 0, v[2:3]
	s_mov_b32 m0, s60
	ds_read_b128 v[178:181], v149 offset:16384
	ds_read_b128 v[182:185], v149 offset:17408
	ds_read_b128 v[186:189], v149 offset:18432
	ds_read_b128 v[190:193], v149 offset:19456
	ds_read_b128 v[194:197], v149 offset:20480
	ds_read_b128 v[202:205], v149 offset:21504
	ds_read_b128 v[206:209], v149 offset:22528
	ds_read_b128 v[210:213], v149 offset:23552
	global_load_lds_dwordx4 v[198:199], off
	s_add_i32 m0, s60, 0x2000
	s_add_u32 s60, s28, 0x40000
	v_lshl_add_u64 v[214:215], s[28:29], 0, v[136:137]
	s_addc_u32 s61, s29, 0
	s_add_i32 s62, s62, s46
	global_load_lds_dwordx4 v[214:215], off
	v_lshl_add_u64 v[216:217], s[60:61], 0, v[2:3]
	s_mov_b32 m0, s62
	v_lshl_add_u64 v[218:219], s[30:31], 0, v[134:135]
	global_load_lds_dwordx4 v[216:217], off
	v_lshl_add_u64 v[216:217], s[60:61], 0, v[136:137]
	s_add_i32 m0, s62, 0x2000
	s_nop 0
	global_load_lds_dwordx4 v[216:217], off
	v_lshl_add_u64 v[216:217], s[30:31], 0, v[132:133]
	s_mov_b32 m0, s47
	s_nop 0
	global_load_lds_dwordx4 v[216:217], off
	s_mov_b32 m0, s48
	s_nop 0
	global_load_lds_dwordx4 v[218:219], off
	s_waitcnt vmcnt(8)
	s_waitcnt lgkmcnt(0)
	s_barrier
	s_waitcnt lgkmcnt(0)
	v_mfma_f32_16x16x32_bf16 v[64:67], v[142:145], v[178:181], v[64:67]
	v_mfma_f32_16x16x32_bf16 v[56:59], v[154:157], v[178:181], v[56:59]
	v_mfma_f32_16x16x32_bf16 v[48:51], v[142:145], v[186:189], v[48:51]
	v_mfma_f32_16x16x32_bf16 v[40:43], v[154:157], v[186:189], v[40:43]
	v_mfma_f32_16x16x32_bf16 v[32:35], v[142:145], v[194:197], v[32:35]
	v_mfma_f32_16x16x32_bf16 v[24:27], v[154:157], v[194:197], v[24:27]
	v_mfma_f32_16x16x32_bf16 v[16:19], v[142:145], v[206:209], v[16:19]
	v_mfma_f32_16x16x32_bf16 v[8:11], v[154:157], v[206:209], v[8:11]
	v_mfma_f32_16x16x32_bf16 v[64:67], v[150:153], v[182:185], v[64:67]
	v_mfma_f32_16x16x32_bf16 v[56:59], v[158:161], v[182:185], v[56:59]
	v_mfma_f32_16x16x32_bf16 v[48:51], v[150:153], v[190:193], v[48:51]
	v_mfma_f32_16x16x32_bf16 v[40:43], v[158:161], v[190:193], v[40:43]
	v_mfma_f32_16x16x32_bf16 v[32:35], v[150:153], v[202:205], v[32:35]
	v_mfma_f32_16x16x32_bf16 v[24:27], v[158:161], v[202:205], v[24:27]
	v_mfma_f32_16x16x32_bf16 v[16:19], v[150:153], v[210:213], v[16:19]
	v_mfma_f32_16x16x32_bf16 v[8:11], v[158:161], v[210:213], v[8:11]
	v_mfma_f32_16x16x32_bf16 v[60:63], v[162:165], v[178:181], v[60:63]
	v_mfma_f32_16x16x32_bf16 v[52:55], v[170:173], v[178:181], v[52:55]
	v_mfma_f32_16x16x32_bf16 v[44:47], v[162:165], v[186:189], v[44:47]
	v_mfma_f32_16x16x32_bf16 v[36:39], v[170:173], v[186:189], v[36:39]
	v_mfma_f32_16x16x32_bf16 v[28:31], v[162:165], v[194:197], v[28:31]
	v_mfma_f32_16x16x32_bf16 v[20:23], v[170:173], v[194:197], v[20:23]
	v_mfma_f32_16x16x32_bf16 v[12:15], v[162:165], v[206:209], v[12:15]
	v_mfma_f32_16x16x32_bf16 v[4:7], v[170:173], v[206:209], v[4:7]
	v_mfma_f32_16x16x32_bf16 v[60:63], v[166:169], v[182:185], v[60:63]
	v_mfma_f32_16x16x32_bf16 v[52:55], v[174:177], v[182:185], v[52:55]
	v_mfma_f32_16x16x32_bf16 v[44:47], v[166:169], v[190:193], v[44:47]
	v_mfma_f32_16x16x32_bf16 v[36:39], v[174:177], v[190:193], v[36:39]
	v_mfma_f32_16x16x32_bf16 v[28:31], v[166:169], v[202:205], v[28:31]
	v_mfma_f32_16x16x32_bf16 v[20:23], v[174:177], v[202:205], v[20:23]
	v_mfma_f32_16x16x32_bf16 v[12:15], v[166:169], v[210:213], v[12:15]
	v_mfma_f32_16x16x32_bf16 v[4:7], v[174:177], v[210:213], v[4:7]
	s_barrier
	s_add_i32 s60, 0, 0x18000
	s_add_i32 s61, 0, 0x1c000
	v_add_u32_e32 v158, s60, v147
	v_add_u32_e32 v174, s61, v147
	ds_read_b128 v[142:145], v158
	ds_read_b128 v[150:153], v158 offset:1024
	ds_read_b128 v[154:157], v158 offset:2048
	ds_read_b128 v[158:161], v158 offset:3072
	ds_read_b128 v[162:165], v174
	ds_read_b128 v[166:169], v174 offset:1024
	ds_read_b128 v[170:173], v174 offset:2048
	ds_read_b128 v[174:177], v174 offset:3072
	s_add_u32 s30, s30, 0x40000
	s_addc_u32 s31, s31, 0
	s_mov_b32 m0, s49
	v_lshl_add_u64 v[220:221], s[30:31], 0, v[132:133]
	ds_read_b128 v[178:181], v149 offset:32768
	ds_read_b128 v[182:185], v149 offset:33792
	ds_read_b128 v[186:189], v149 offset:34816
	ds_read_b128 v[190:193], v149 offset:35840
	ds_read_b128 v[194:197], v149 offset:36864
	ds_read_b128 v[202:205], v149 offset:37888
	ds_read_b128 v[206:209], v149 offset:38912
	ds_read_b128 v[210:213], v149 offset:39936
	global_load_lds_dwordx4 v[220:221], off
	v_lshl_add_u64 v[220:221], s[30:31], 0, v[134:135]
	s_mov_b32 m0, s50
	s_nop 0
	global_load_lds_dwordx4 v[220:221], off
	s_waitcnt vmcnt(8)
	s_waitcnt lgkmcnt(0)
	s_barrier
	s_waitcnt lgkmcnt(0)
	v_mfma_f32_16x16x32_bf16 v[128:131], v[142:145], v[178:181], v[128:131]
	v_mfma_f32_16x16x32_bf16 v[120:123], v[154:157], v[178:181], v[120:123]
	v_mfma_f32_16x16x32_bf16 v[112:115], v[142:145], v[186:189], v[112:115]
	v_mfma_f32_16x16x32_bf16 v[104:107], v[154:157], v[186:189], v[104:107]
	v_mfma_f32_16x16x32_bf16 v[96:99], v[142:145], v[194:197], v[96:99]
	v_mfma_f32_16x16x32_bf16 v[88:91], v[154:157], v[194:197], v[88:91]
	v_mfma_f32_16x16x32_bf16 v[80:83], v[142:145], v[206:209], v[80:83]
	v_mfma_f32_16x16x32_bf16 v[72:75], v[154:157], v[206:209], v[72:75]
	v_mfma_f32_16x16x32_bf16 v[128:131], v[150:153], v[182:185], v[128:131]
	v_mfma_f32_16x16x32_bf16 v[120:123], v[158:161], v[182:185], v[120:123]
	v_mfma_f32_16x16x32_bf16 v[112:115], v[150:153], v[190:193], v[112:115]
	v_mfma_f32_16x16x32_bf16 v[104:107], v[158:161], v[190:193], v[104:107]
	v_mfma_f32_16x16x32_bf16 v[96:99], v[150:153], v[202:205], v[96:99]
	v_mfma_f32_16x16x32_bf16 v[88:91], v[158:161], v[202:205], v[88:91]
	v_mfma_f32_16x16x32_bf16 v[80:83], v[150:153], v[210:213], v[80:83]
	v_mfma_f32_16x16x32_bf16 v[72:75], v[158:161], v[210:213], v[72:75]
	v_mfma_f32_16x16x32_bf16 v[124:127], v[162:165], v[178:181], v[124:127]
	v_mfma_f32_16x16x32_bf16 v[116:119], v[170:173], v[178:181], v[116:119]
	v_mfma_f32_16x16x32_bf16 v[108:111], v[162:165], v[186:189], v[108:111]
	v_mfma_f32_16x16x32_bf16 v[100:103], v[170:173], v[186:189], v[100:103]
	v_mfma_f32_16x16x32_bf16 v[92:95], v[162:165], v[194:197], v[92:95]
	v_mfma_f32_16x16x32_bf16 v[84:87], v[170:173], v[194:197], v[84:87]
	v_mfma_f32_16x16x32_bf16 v[76:79], v[162:165], v[206:209], v[76:79]
	v_mfma_f32_16x16x32_bf16 v[68:71], v[170:173], v[206:209], v[68:71]
	v_mfma_f32_16x16x32_bf16 v[124:127], v[166:169], v[182:185], v[124:127]
	v_mfma_f32_16x16x32_bf16 v[116:119], v[174:177], v[182:185], v[116:119]
	v_mfma_f32_16x16x32_bf16 v[108:111], v[166:169], v[190:193], v[108:111]
	v_mfma_f32_16x16x32_bf16 v[100:103], v[174:177], v[190:193], v[100:103]
	v_mfma_f32_16x16x32_bf16 v[92:95], v[166:169], v[202:205], v[92:95]
	v_mfma_f32_16x16x32_bf16 v[84:87], v[174:177], v[202:205], v[84:87]
	v_mfma_f32_16x16x32_bf16 v[76:79], v[166:169], v[210:213], v[76:79]
	v_mfma_f32_16x16x32_bf16 v[68:71], v[174:177], v[210:213], v[68:71]
	s_barrier
	s_add_i32 s30, s60, s46
	v_lshl_add_u64 v[198:199], v[198:199], 0, s[66:67]
	s_mov_b32 m0, s30
	ds_read_b128 v[178:181], v149 offset:49152
	ds_read_b128 v[182:185], v149 offset:50176
	ds_read_b128 v[186:189], v149 offset:51200
	ds_read_b128 v[190:193], v149 offset:52224
	ds_read_b128 v[194:197], v149 offset:53248
	ds_read_b128 v[202:205], v149 offset:54272
	ds_read_b128 v[206:209], v149 offset:55296
	ds_read_b128 v[210:213], v149 offset:56320
	global_load_lds_dwordx4 v[198:199], off
	s_add_i32 m0, s30, 0x2000
	s_add_u32 s28, s28, 0x40080
	v_lshl_add_u64 v[198:199], v[214:215], 0, s[66:67]
	s_addc_u32 s29, s29, 0
	s_add_i32 s30, s61, s46
	global_load_lds_dwordx4 v[198:199], off
	v_lshl_add_u64 v[198:199], s[28:29], 0, v[2:3]
	s_mov_b32 m0, s30
	s_nop 0
	global_load_lds_dwordx4 v[198:199], off
	v_lshl_add_u64 v[198:199], s[28:29], 0, v[136:137]
	s_add_i32 m0, s30, 0x2000
	s_nop 0
	global_load_lds_dwordx4 v[198:199], off
	v_lshl_add_u64 v[198:199], v[216:217], 0, s[66:67]
	s_mov_b32 m0, s51
	s_nop 0
	global_load_lds_dwordx4 v[198:199], off
	v_lshl_add_u64 v[198:199], v[218:219], 0, s[66:67]
	s_mov_b32 m0, s52
	s_nop 0
	global_load_lds_dwordx4 v[198:199], off
	s_waitcnt vmcnt(8)
	s_waitcnt lgkmcnt(0)
	s_barrier
	s_waitcnt lgkmcnt(0)
	v_mfma_f32_16x16x32_bf16 v[64:67], v[142:145], v[178:181], v[64:67]
	v_mfma_f32_16x16x32_bf16 v[56:59], v[154:157], v[178:181], v[56:59]
	v_mfma_f32_16x16x32_bf16 v[48:51], v[142:145], v[186:189], v[48:51]
	v_mfma_f32_16x16x32_bf16 v[40:43], v[154:157], v[186:189], v[40:43]
	v_mfma_f32_16x16x32_bf16 v[32:35], v[142:145], v[194:197], v[32:35]
	v_mfma_f32_16x16x32_bf16 v[24:27], v[154:157], v[194:197], v[24:27]
	v_mfma_f32_16x16x32_bf16 v[16:19], v[142:145], v[206:209], v[16:19]
	v_mfma_f32_16x16x32_bf16 v[8:11], v[154:157], v[206:209], v[8:11]
	v_mfma_f32_16x16x32_bf16 v[64:67], v[150:153], v[182:185], v[64:67]
	v_mfma_f32_16x16x32_bf16 v[56:59], v[158:161], v[182:185], v[56:59]
	v_mfma_f32_16x16x32_bf16 v[48:51], v[150:153], v[190:193], v[48:51]
	v_mfma_f32_16x16x32_bf16 v[40:43], v[158:161], v[190:193], v[40:43]
	v_mfma_f32_16x16x32_bf16 v[32:35], v[150:153], v[202:205], v[32:35]
	v_mfma_f32_16x16x32_bf16 v[24:27], v[158:161], v[202:205], v[24:27]
	v_mfma_f32_16x16x32_bf16 v[16:19], v[150:153], v[210:213], v[16:19]
	v_mfma_f32_16x16x32_bf16 v[8:11], v[158:161], v[210:213], v[8:11]
	v_mfma_f32_16x16x32_bf16 v[60:63], v[162:165], v[178:181], v[60:63]
	v_mfma_f32_16x16x32_bf16 v[52:55], v[170:173], v[178:181], v[52:55]
	v_mfma_f32_16x16x32_bf16 v[44:47], v[162:165], v[186:189], v[44:47]
	v_mfma_f32_16x16x32_bf16 v[36:39], v[170:173], v[186:189], v[36:39]
	v_mfma_f32_16x16x32_bf16 v[28:31], v[162:165], v[194:197], v[28:31]
	v_mfma_f32_16x16x32_bf16 v[20:23], v[170:173], v[194:197], v[20:23]
	v_mfma_f32_16x16x32_bf16 v[12:15], v[162:165], v[206:209], v[12:15]
	v_mfma_f32_16x16x32_bf16 v[4:7], v[170:173], v[206:209], v[4:7]
	v_mfma_f32_16x16x32_bf16 v[60:63], v[166:169], v[182:185], v[60:63]
	v_mfma_f32_16x16x32_bf16 v[52:55], v[174:177], v[182:185], v[52:55]
	v_mfma_f32_16x16x32_bf16 v[44:47], v[166:169], v[190:193], v[44:47]
	v_mfma_f32_16x16x32_bf16 v[36:39], v[174:177], v[190:193], v[36:39]
	v_mfma_f32_16x16x32_bf16 v[28:31], v[166:169], v[202:205], v[28:31]
	v_mfma_f32_16x16x32_bf16 v[20:23], v[174:177], v[202:205], v[20:23]
	v_mfma_f32_16x16x32_bf16 v[12:15], v[166:169], v[210:213], v[12:15]
	v_mfma_f32_16x16x32_bf16 v[4:7], v[174:177], v[210:213], v[4:7]
	s_barrier
	s_add_i32 s59, s59, 2
	s_add_u32 s26, s26, 0x100
	s_addc_u32 s27, s27, 0
	s_add_u32 s57, s57, 0x100
	s_addc_u32 s58, s58, 0
	s_cmp_gt_u32 s59, 13
	s_cbranch_scc0 .LBB0_1575
	s_setprio 0
	s_and_b64 vcc, exec, s[14:15]
	s_mov_b64 s[58:59], 0x9300380
	s_cbranch_vccz .LBB0_1578
	s_barrier

.LBB0_1604:
	v_lshrrev_b32_e32 v16, 1, v9
	v_and_b32_e32 v142, 24, v16
	v_and_b32_e32 v15, 15, v9
	v_lshlrev_b32_e32 v16, 1, v142
	v_lshlrev_b32_e32 v9, 2, v9
	v_lshl_or_b32 v1, s8, 6, v15
	s_lshl_b32 s8, s8, 13
	v_lshl_or_b32 v15, v15, 6, v16
	v_and_b32_e32 v9, 32, v9
	v_bitop3_b32 v16, v15, s8, v9 bitop3:0xde
	s_lshl_b32 s8, s10, 5
	s_mov_b64 s[30:31], 0x80
	s_and_b32 s21, s8, 0x60
	s_add_i32 m0, s17, 0x18000
	v_lshl_add_u64 v[4:5], v[4:5], 0, s[30:31]
	s_lshl_b32 s8, s21, 7
	s_waitcnt vmcnt(2)
	s_barrier
	global_load_lds_dwordx4 v[4:5], off
	s_add_i32 m0, s17, 0x1a000
	s_add_u32 s10, s2, 0xc000080
	v_mov_b32_e32 v133, v3
	v_lshl_add_u64 v[4:5], v[6:7], 0, s[30:31]
	s_addc_u32 s11, s3, 0
	s_add_i32 s22, s17, 0x8000
	v_mov_b32_e32 v135, v3
	global_load_lds_dwordx4 v[4:5], off
	v_lshl_add_u64 v[4:5], s[10:11], 0, v[132:133]
	s_mov_b32 m0, s22
	s_add_i32 s23, s17, 0xa000
	global_load_lds_dwordx4 v[4:5], off
	v_lshl_add_u64 v[4:5], s[10:11], 0, v[134:135]
	s_add_u32 s10, s6, 0x40080
	s_mov_b32 m0, s23
	s_addc_u32 s11, s7, 0
	global_load_lds_dwordx4 v[4:5], off
	s_add_i32 m0, s17, 0x1c000
	v_lshl_add_u64 v[4:5], s[10:11], 0, v[2:3]
	global_load_lds_dwordx4 v[4:5], off
	v_lshl_add_u64 v[4:5], s[10:11], 0, v[136:137]
	s_add_i32 m0, s17, 0x1e000
	s_mov_b64 s[10:11], 0xc040080
	global_load_lds_dwordx4 v[4:5], off
	v_lshlrev_b32_e32 v4, 14, v8
	v_and_b32_e32 v4, 0xffff8000, v4
	v_lshl_add_u32 v4, v10, 11, v4
	v_and_b32_e32 v5, 1, v8
	v_lshl_or_b32 v4, v5, 6, v4
	v_lshl_add_u32 v4, v11, 1, v4
	v_mov_b32_e32 v5, v3
	v_lshl_add_u64 v[138:139], v[4:5], 0, s[10:11]
	v_lshlrev_b32_e32 v4, 14, v12
	v_and_b32_e32 v4, 0xffff8000, v4
	v_lshl_add_u32 v4, v13, 11, v4
	v_and_b32_e32 v5, 1, v12
	v_lshl_or_b32 v4, v5, 6, v4
	v_lshl_add_u32 v4, v14, 1, v4
	v_mov_b32_e32 v5, v3
	s_waitcnt vmcnt(6)
	v_lshl_add_u64 v[140:141], v[4:5], 0, s[10:11]
	v_readlane_b32 s10, v254, 25
	v_readlane_b32 s11, v254, 26
	s_add_u32 s24, s10, s9
	v_mov_b32_e32 v4, 0
	v_bitop3_b32 v143, v15, s8, v9 bitop3:0xde
	s_addc_u32 s25, s11, 0
	s_mov_b32 s26, -2
	v_add_u32_e32 v144, 0, v16
	s_mov_b64 s[8:9], s[2:3]
	v_mov_b32_e32 v5, v4
	v_mov_b32_e32 v6, v4
	v_mov_b32_e32 v7, v4
	v_mov_b32_e32 v12, v4
	v_mov_b32_e32 v13, v4
	v_mov_b32_e32 v14, v4
	v_mov_b32_e32 v15, v4
	v_mov_b32_e32 v20, v4
	v_mov_b32_e32 v21, v4
	v_mov_b32_e32 v22, v4
	v_mov_b32_e32 v23, v4
	v_mov_b32_e32 v28, v4
	v_mov_b32_e32 v29, v4
	v_mov_b32_e32 v30, v4
	v_mov_b32_e32 v31, v4
	v_mov_b32_e32 v36, v4
	v_mov_b32_e32 v37, v4
	v_mov_b32_e32 v38, v4
	v_mov_b32_e32 v39, v4
	v_mov_b32_e32 v44, v4
	v_mov_b32_e32 v45, v4
	v_mov_b32_e32 v46, v4
	v_mov_b32_e32 v47, v4
	v_mov_b32_e32 v52, v4
	v_mov_b32_e32 v53, v4
	v_mov_b32_e32 v54, v4
	v_mov_b32_e32 v55, v4
	v_mov_b32_e32 v60, v4
	v_mov_b32_e32 v61, v4
	v_mov_b32_e32 v62, v4
	v_mov_b32_e32 v63, v4
	v_mov_b32_e32 v8, v4
	v_mov_b32_e32 v9, v4
	v_mov_b32_e32 v10, v4
	v_mov_b32_e32 v11, v4
	v_mov_b32_e32 v16, v4
	v_mov_b32_e32 v17, v4
	v_mov_b32_e32 v18, v4
	v_mov_b32_e32 v19, v4
	v_mov_b32_e32 v24, v4
	v_mov_b32_e32 v25, v4
	v_mov_b32_e32 v26, v4
	v_mov_b32_e32 v27, v4
	v_mov_b32_e32 v32, v4
	v_mov_b32_e32 v33, v4
	v_mov_b32_e32 v34, v4
	v_mov_b32_e32 v35, v4
	v_mov_b32_e32 v40, v4
	v_mov_b32_e32 v41, v4
	v_mov_b32_e32 v42, v4
	v_mov_b32_e32 v43, v4
	v_mov_b32_e32 v48, v4
	v_mov_b32_e32 v49, v4
	v_mov_b32_e32 v50, v4
	v_mov_b32_e32 v51, v4
	v_mov_b32_e32 v56, v4
	v_mov_b32_e32 v57, v4
	v_mov_b32_e32 v58, v4
	v_mov_b32_e32 v59, v4
	v_mov_b32_e32 v64, v4
	v_mov_b32_e32 v65, v4
	v_mov_b32_e32 v66, v4
	v_mov_b32_e32 v67, v4
	v_mov_b32_e32 v68, v4
	v_mov_b32_e32 v69, v4
	v_mov_b32_e32 v70, v4
	v_mov_b32_e32 v71, v4
	v_mov_b32_e32 v76, v4
	v_mov_b32_e32 v77, v4
	v_mov_b32_e32 v78, v4
	v_mov_b32_e32 v79, v4
	v_mov_b32_e32 v84, v4
	v_mov_b32_e32 v85, v4
	v_mov_b32_e32 v86, v4
	v_mov_b32_e32 v87, v4
	v_mov_b32_e32 v92, v4
	v_mov_b32_e32 v93, v4
	v_mov_b32_e32 v94, v4
	v_mov_b32_e32 v95, v4
	v_mov_b32_e32 v100, v4
	v_mov_b32_e32 v101, v4
	v_mov_b32_e32 v102, v4
	v_mov_b32_e32 v103, v4
	v_mov_b32_e32 v108, v4
	v_mov_b32_e32 v109, v4
	v_mov_b32_e32 v110, v4
	v_mov_b32_e32 v111, v4
	v_mov_b32_e32 v116, v4
	v_mov_b32_e32 v117, v4
	v_mov_b32_e32 v118, v4
	v_mov_b32_e32 v119, v4
	v_mov_b32_e32 v124, v4
	v_mov_b32_e32 v125, v4
	v_mov_b32_e32 v126, v4
	v_mov_b32_e32 v127, v4
	v_mov_b32_e32 v72, v4
	v_mov_b32_e32 v73, v4
	v_mov_b32_e32 v74, v4
	v_mov_b32_e32 v75, v4
	v_mov_b32_e32 v80, v4
	v_mov_b32_e32 v81, v4
	v_mov_b32_e32 v82, v4
	v_mov_b32_e32 v83, v4
	v_mov_b32_e32 v88, v4
	v_mov_b32_e32 v89, v4
	v_mov_b32_e32 v90, v4
	v_mov_b32_e32 v91, v4
	v_mov_b32_e32 v96, v4
	v_mov_b32_e32 v97, v4
	v_mov_b32_e32 v98, v4
	v_mov_b32_e32 v99, v4
	v_mov_b32_e32 v104, v4
	v_mov_b32_e32 v105, v4
	v_mov_b32_e32 v106, v4
	v_mov_b32_e32 v107, v4
	v_mov_b32_e32 v112, v4
	v_mov_b32_e32 v113, v4
	v_mov_b32_e32 v114, v4
	v_mov_b32_e32 v115, v4
	v_mov_b32_e32 v120, v4
	v_mov_b32_e32 v121, v4
	v_mov_b32_e32 v122, v4
	v_mov_b32_e32 v123, v4
	v_mov_b32_e32 v128, v4
	v_mov_b32_e32 v129, v4
	v_mov_b32_e32 v130, v4
	v_mov_b32_e32 v131, v4
	s_barrier
	v_readfirstlane_b32 s100, v0
	s_cmp_lt_u32 s100, 0x100
	s_cbranch_scc1 .Lgprio_2
	s_setprio 1
.Lgprio_2:
.LBB0_1605:
	s_add_u32 s10, s8, 0xc000100
	s_addc_u32 s11, s9, 0
	s_add_u32 s27, s8, s24
	s_addc_u32 s28, s9, s25
	s_add_i32 s29, 0, 0x10000
	s_cmp_eq_u32 s26, 12
	s_cselect_b32 s13, s5, s11
	s_cselect_b32 s12, s4, s10
	v_add_u32_e32 v145, s29, v143
	s_cselect_b32 s11, s7, s28
	s_cselect_b32 s10, s6, s27
	s_add_i32 s27, 0, 0x14000
	ds_read_b128 v[146:149], v145
	ds_read_b128 v[150:153], v145 offset:1024
	ds_read_b128 v[154:157], v145 offset:2048
	ds_read_b128 v[158:161], v145 offset:3072
	v_add_u32_e32 v145, s27, v143
	ds_read_b128 v[162:165], v145
	ds_read_b128 v[166:169], v145 offset:1024
	ds_read_b128 v[170:173], v145 offset:2048
	ds_read_b128 v[174:177], v145 offset:3072
	v_lshl_add_u64 v[198:199], s[8:9], 0, v[138:139]
	s_add_i32 m0, s17, 0xc000
	ds_read_b128 v[178:181], v144
	ds_read_b128 v[182:185], v144 offset:1024
	ds_read_b128 v[186:189], v144 offset:2048
	ds_read_b128 v[190:193], v144 offset:3072
	ds_read_b128 v[194:197], v144 offset:4096
	ds_read_b128 v[202:205], v144 offset:5120
	ds_read_b128 v[206:209], v144 offset:6144
	ds_read_b128 v[210:213], v144 offset:7168
	global_load_lds_dwordx4 v[198:199], off
	v_lshl_add_u64 v[198:199], s[8:9], 0, v[140:141]
	s_add_i32 m0, s17, 0xe000
	s_nop 0
	global_load_lds_dwordx4 v[198:199], off
	s_waitcnt vmcnt(8)
	s_waitcnt lgkmcnt(0)
	s_barrier
	s_waitcnt lgkmcnt(0)
	v_mfma_f32_16x16x32_bf16 v[128:131], v[146:149], v[178:181], v[128:131]
	v_mfma_f32_16x16x32_bf16 v[120:123], v[154:157], v[178:181], v[120:123]
	v_mfma_f32_16x16x32_bf16 v[112:115], v[146:149], v[186:189], v[112:115]
	v_mfma_f32_16x16x32_bf16 v[104:107], v[154:157], v[186:189], v[104:107]
	v_mfma_f32_16x16x32_bf16 v[96:99], v[146:149], v[194:197], v[96:99]
	v_mfma_f32_16x16x32_bf16 v[88:91], v[154:157], v[194:197], v[88:91]
	v_mfma_f32_16x16x32_bf16 v[80:83], v[146:149], v[206:209], v[80:83]
	v_mfma_f32_16x16x32_bf16 v[72:75], v[154:157], v[206:209], v[72:75]
	v_mfma_f32_16x16x32_bf16 v[128:131], v[150:153], v[182:185], v[128:131]
	v_mfma_f32_16x16x32_bf16 v[120:123], v[158:161], v[182:185], v[120:123]
	v_mfma_f32_16x16x32_bf16 v[112:115], v[150:153], v[190:193], v[112:115]
	v_mfma_f32_16x16x32_bf16 v[104:107], v[158:161], v[190:193], v[104:107]
	v_mfma_f32_16x16x32_bf16 v[96:99], v[150:153], v[202:205], v[96:99]
	v_mfma_f32_16x16x32_bf16 v[88:91], v[158:161], v[202:205], v[88:91]
	v_mfma_f32_16x16x32_bf16 v[80:83], v[150:153], v[210:213], v[80:83]
	v_mfma_f32_16x16x32_bf16 v[72:75], v[158:161], v[210:213], v[72:75]
	v_mfma_f32_16x16x32_bf16 v[124:127], v[162:165], v[178:181], v[124:127]
	v_mfma_f32_16x16x32_bf16 v[116:119], v[170:173], v[178:181], v[116:119]
	v_mfma_f32_16x16x32_bf16 v[108:111], v[162:165], v[186:189], v[108:111]
	v_mfma_f32_16x16x32_bf16 v[100:103], v[170:173], v[186:189], v[100:103]
	v_mfma_f32_16x16x32_bf16 v[92:95], v[162:165], v[194:197], v[92:95]
	v_mfma_f32_16x16x32_bf16 v[84:87], v[170:173], v[194:197], v[84:87]
	v_mfma_f32_16x16x32_bf16 v[76:79], v[162:165], v[206:209], v[76:79]
	v_mfma_f32_16x16x32_bf16 v[68:71], v[170:173], v[206:209], v[68:71]
	v_mfma_f32_16x16x32_bf16 v[124:127], v[166:169], v[182:185], v[124:127]
	v_mfma_f32_16x16x32_bf16 v[116:119], v[174:177], v[182:185], v[116:119]
	v_mfma_f32_16x16x32_bf16 v[108:111], v[166:169], v[190:193], v[108:111]
	v_mfma_f32_16x16x32_bf16 v[100:103], v[174:177], v[190:193], v[100:103]
	v_mfma_f32_16x16x32_bf16 v[92:95], v[166:169], v[202:205], v[92:95]
	v_mfma_f32_16x16x32_bf16 v[84:87], v[174:177], v[202:205], v[84:87]
	v_mfma_f32_16x16x32_bf16 v[76:79], v[166:169], v[210:213], v[76:79]
	v_mfma_f32_16x16x32_bf16 v[68:71], v[174:177], v[210:213], v[68:71]
	s_barrier
	s_add_i32 s28, s29, s16
	v_lshl_add_u64 v[198:199], s[10:11], 0, v[2:3]
	s_mov_b32 m0, s28
	ds_read_b128 v[178:181], v144 offset:16384
	ds_read_b128 v[182:185], v144 offset:17408
	ds_read_b128 v[186:189], v144 offset:18432
	ds_read_b128 v[190:193], v144 offset:19456
	ds_read_b128 v[194:197], v144 offset:20480
	ds_read_b128 v[202:205], v144 offset:21504
	ds_read_b128 v[206:209], v144 offset:22528
	ds_read_b128 v[210:213], v144 offset:23552
	global_load_lds_dwordx4 v[198:199], off
	s_add_i32 m0, s28, 0x2000
	s_add_u32 s28, s10, 0x40000
	v_lshl_add_u64 v[214:215], s[10:11], 0, v[136:137]
	s_addc_u32 s29, s11, 0
	s_add_i32 s27, s27, s16
	global_load_lds_dwordx4 v[214:215], off
	v_lshl_add_u64 v[216:217], s[28:29], 0, v[2:3]
	s_mov_b32 m0, s27
	v_lshl_add_u64 v[218:219], s[12:13], 0, v[134:135]
	global_load_lds_dwordx4 v[216:217], off
	v_lshl_add_u64 v[216:217], s[28:29], 0, v[136:137]
	s_add_i32 m0, s27, 0x2000
	s_nop 0
	global_load_lds_dwordx4 v[216:217], off
	v_lshl_add_u64 v[216:217], s[12:13], 0, v[132:133]
	s_mov_b32 m0, s17
	s_nop 0
	global_load_lds_dwordx4 v[216:217], off
	s_mov_b32 m0, s18
	s_nop 0
	global_load_lds_dwordx4 v[218:219], off
	s_waitcnt vmcnt(8)
	s_waitcnt lgkmcnt(0)
	s_barrier
	s_waitcnt lgkmcnt(0)
	v_mfma_f32_16x16x32_bf16 v[64:67], v[146:149], v[178:181], v[64:67]
	v_mfma_f32_16x16x32_bf16 v[56:59], v[154:157], v[178:181], v[56:59]
	v_mfma_f32_16x16x32_bf16 v[48:51], v[146:149], v[186:189], v[48:51]
	v_mfma_f32_16x16x32_bf16 v[40:43], v[154:157], v[186:189], v[40:43]
	v_mfma_f32_16x16x32_bf16 v[32:35], v[146:149], v[194:197], v[32:35]
	v_mfma_f32_16x16x32_bf16 v[24:27], v[154:157], v[194:197], v[24:27]
	v_mfma_f32_16x16x32_bf16 v[16:19], v[146:149], v[206:209], v[16:19]
	v_mfma_f32_16x16x32_bf16 v[8:11], v[154:157], v[206:209], v[8:11]
	v_mfma_f32_16x16x32_bf16 v[64:67], v[150:153], v[182:185], v[64:67]
	v_mfma_f32_16x16x32_bf16 v[56:59], v[158:161], v[182:185], v[56:59]
	v_mfma_f32_16x16x32_bf16 v[48:51], v[150:153], v[190:193], v[48:51]
	v_mfma_f32_16x16x32_bf16 v[40:43], v[158:161], v[190:193], v[40:43]
	v_mfma_f32_16x16x32_bf16 v[32:35], v[150:153], v[202:205], v[32:35]
	v_mfma_f32_16x16x32_bf16 v[24:27], v[158:161], v[202:205], v[24:27]
	v_mfma_f32_16x16x32_bf16 v[16:19], v[150:153], v[210:213], v[16:19]
	v_mfma_f32_16x16x32_bf16 v[8:11], v[158:161], v[210:213], v[8:11]
	v_mfma_f32_16x16x32_bf16 v[60:63], v[162:165], v[178:181], v[60:63]
	v_mfma_f32_16x16x32_bf16 v[52:55], v[170:173], v[178:181], v[52:55]
	v_mfma_f32_16x16x32_bf16 v[44:47], v[162:165], v[186:189], v[44:47]
	v_mfma_f32_16x16x32_bf16 v[36:39], v[170:173], v[186:189], v[36:39]
	v_mfma_f32_16x16x32_bf16 v[28:31], v[162:165], v[194:197], v[28:31]
	v_mfma_f32_16x16x32_bf16 v[20:23], v[170:173], v[194:197], v[20:23]
	v_mfma_f32_16x16x32_bf16 v[12:15], v[162:165], v[206:209], v[12:15]
	v_mfma_f32_16x16x32_bf16 v[4:7], v[170:173], v[206:209], v[4:7]
	v_mfma_f32_16x16x32_bf16 v[60:63], v[166:169], v[182:185], v[60:63]
	v_mfma_f32_16x16x32_bf16 v[52:55], v[174:177], v[182:185], v[52:55]
	v_mfma_f32_16x16x32_bf16 v[44:47], v[166:169], v[190:193], v[44:47]
	v_mfma_f32_16x16x32_bf16 v[36:39], v[174:177], v[190:193], v[36:39]
	v_mfma_f32_16x16x32_bf16 v[28:31], v[166:169], v[202:205], v[28:31]
	v_mfma_f32_16x16x32_bf16 v[20:23], v[174:177], v[202:205], v[20:23]
	v_mfma_f32_16x16x32_bf16 v[12:15], v[166:169], v[210:213], v[12:15]
	v_mfma_f32_16x16x32_bf16 v[4:7], v[174:177], v[210:213], v[4:7]
	s_barrier
	s_add_i32 s27, 0, 0x18000
	v_add_u32_e32 v145, s27, v143
	s_add_i32 s28, 0, 0x1c000
	ds_read_b128 v[146:149], v145
	ds_read_b128 v[150:153], v145 offset:1024
	ds_read_b128 v[154:157], v145 offset:2048
	ds_read_b128 v[158:161], v145 offset:3072
	v_add_u32_e32 v145, s28, v143
	ds_read_b128 v[162:165], v145
	ds_read_b128 v[166:169], v145 offset:1024
	ds_read_b128 v[170:173], v145 offset:2048
	ds_read_b128 v[174:177], v145 offset:3072
	s_add_u32 s12, s12, 0x40000
	s_addc_u32 s13, s13, 0
	s_mov_b32 m0, s19
	v_lshl_add_u64 v[220:221], s[12:13], 0, v[132:133]
	ds_read_b128 v[178:181], v144 offset:32768
	ds_read_b128 v[182:185], v144 offset:33792
	ds_read_b128 v[186:189], v144 offset:34816
	ds_read_b128 v[190:193], v144 offset:35840
	ds_read_b128 v[194:197], v144 offset:36864
	ds_read_b128 v[202:205], v144 offset:37888
	ds_read_b128 v[206:209], v144 offset:38912
	ds_read_b128 v[210:213], v144 offset:39936
	global_load_lds_dwordx4 v[220:221], off
	v_lshl_add_u64 v[220:221], s[12:13], 0, v[134:135]
	s_mov_b32 m0, s20
	s_nop 0
	global_load_lds_dwordx4 v[220:221], off
	s_waitcnt vmcnt(8)
	s_waitcnt lgkmcnt(0)
	s_barrier
	s_waitcnt lgkmcnt(0)
	v_mfma_f32_16x16x32_bf16 v[128:131], v[146:149], v[178:181], v[128:131]
	v_mfma_f32_16x16x32_bf16 v[120:123], v[154:157], v[178:181], v[120:123]
	v_mfma_f32_16x16x32_bf16 v[112:115], v[146:149], v[186:189], v[112:115]
	v_mfma_f32_16x16x32_bf16 v[104:107], v[154:157], v[186:189], v[104:107]
	v_mfma_f32_16x16x32_bf16 v[96:99], v[146:149], v[194:197], v[96:99]
	v_mfma_f32_16x16x32_bf16 v[88:91], v[154:157], v[194:197], v[88:91]
	v_mfma_f32_16x16x32_bf16 v[80:83], v[146:149], v[206:209], v[80:83]
	v_mfma_f32_16x16x32_bf16 v[72:75], v[154:157], v[206:209], v[72:75]
	v_mfma_f32_16x16x32_bf16 v[128:131], v[150:153], v[182:185], v[128:131]
	v_mfma_f32_16x16x32_bf16 v[120:123], v[158:161], v[182:185], v[120:123]
	v_mfma_f32_16x16x32_bf16 v[112:115], v[150:153], v[190:193], v[112:115]
	v_mfma_f32_16x16x32_bf16 v[104:107], v[158:161], v[190:193], v[104:107]
	v_mfma_f32_16x16x32_bf16 v[96:99], v[150:153], v[202:205], v[96:99]
	v_mfma_f32_16x16x32_bf16 v[88:91], v[158:161], v[202:205], v[88:91]
	v_mfma_f32_16x16x32_bf16 v[80:83], v[150:153], v[210:213], v[80:83]
	v_mfma_f32_16x16x32_bf16 v[72:75], v[158:161], v[210:213], v[72:75]
	v_mfma_f32_16x16x32_bf16 v[124:127], v[162:165], v[178:181], v[124:127]
	v_mfma_f32_16x16x32_bf16 v[116:119], v[170:173], v[178:181], v[116:119]
	v_mfma_f32_16x16x32_bf16 v[108:111], v[162:165], v[186:189], v[108:111]
	v_mfma_f32_16x16x32_bf16 v[100:103], v[170:173], v[186:189], v[100:103]
	v_mfma_f32_16x16x32_bf16 v[92:95], v[162:165], v[194:197], v[92:95]
	v_mfma_f32_16x16x32_bf16 v[84:87], v[170:173], v[194:197], v[84:87]
	v_mfma_f32_16x16x32_bf16 v[76:79], v[162:165], v[206:209], v[76:79]
	v_mfma_f32_16x16x32_bf16 v[68:71], v[170:173], v[206:209], v[68:71]
	v_mfma_f32_16x16x32_bf16 v[124:127], v[166:169], v[182:185], v[124:127]
	v_mfma_f32_16x16x32_bf16 v[116:119], v[174:177], v[182:185], v[116:119]
	v_mfma_f32_16x16x32_bf16 v[108:111], v[166:169], v[190:193], v[108:111]
	v_mfma_f32_16x16x32_bf16 v[100:103], v[174:177], v[190:193], v[100:103]
	v_mfma_f32_16x16x32_bf16 v[92:95], v[166:169], v[202:205], v[92:95]
	v_mfma_f32_16x16x32_bf16 v[84:87], v[174:177], v[202:205], v[84:87]
	v_mfma_f32_16x16x32_bf16 v[76:79], v[166:169], v[210:213], v[76:79]
	v_mfma_f32_16x16x32_bf16 v[68:71], v[174:177], v[210:213], v[68:71]
	s_barrier
	s_add_i32 s12, s27, s16
	v_lshl_add_u64 v[198:199], v[198:199], 0, s[30:31]
	s_mov_b32 m0, s12
	ds_read_b128 v[178:181], v144 offset:49152
	ds_read_b128 v[182:185], v144 offset:50176
	ds_read_b128 v[186:189], v144 offset:51200
	ds_read_b128 v[190:193], v144 offset:52224
	ds_read_b128 v[194:197], v144 offset:53248
	ds_read_b128 v[202:205], v144 offset:54272
	ds_read_b128 v[206:209], v144 offset:55296
	ds_read_b128 v[210:213], v144 offset:56320
	global_load_lds_dwordx4 v[198:199], off
	s_add_i32 m0, s12, 0x2000
	s_add_u32 s10, s10, 0x40080
	v_lshl_add_u64 v[198:199], v[214:215], 0, s[30:31]
	s_addc_u32 s11, s11, 0
	s_add_i32 s12, s28, s16
	global_load_lds_dwordx4 v[198:199], off
	v_lshl_add_u64 v[198:199], s[10:11], 0, v[2:3]
	s_mov_b32 m0, s12
	s_nop 0
	global_load_lds_dwordx4 v[198:199], off
	v_lshl_add_u64 v[198:199], s[10:11], 0, v[136:137]
	s_add_i32 m0, s12, 0x2000
	s_nop 0
	global_load_lds_dwordx4 v[198:199], off
	v_lshl_add_u64 v[198:199], v[216:217], 0, s[30:31]
	s_mov_b32 m0, s22
	s_nop 0
	global_load_lds_dwordx4 v[198:199], off
	v_lshl_add_u64 v[198:199], v[218:219], 0, s[30:31]
	s_mov_b32 m0, s23
	s_nop 0
	global_load_lds_dwordx4 v[198:199], off
	s_waitcnt vmcnt(8)
	s_waitcnt lgkmcnt(0)
	s_barrier
	s_waitcnt lgkmcnt(0)
	v_mfma_f32_16x16x32_bf16 v[64:67], v[146:149], v[178:181], v[64:67]
	v_mfma_f32_16x16x32_bf16 v[56:59], v[154:157], v[178:181], v[56:59]
	v_mfma_f32_16x16x32_bf16 v[48:51], v[146:149], v[186:189], v[48:51]
	v_mfma_f32_16x16x32_bf16 v[40:43], v[154:157], v[186:189], v[40:43]
	v_mfma_f32_16x16x32_bf16 v[32:35], v[146:149], v[194:197], v[32:35]
	v_mfma_f32_16x16x32_bf16 v[24:27], v[154:157], v[194:197], v[24:27]
	v_mfma_f32_16x16x32_bf16 v[16:19], v[146:149], v[206:209], v[16:19]
	v_mfma_f32_16x16x32_bf16 v[8:11], v[154:157], v[206:209], v[8:11]
	v_mfma_f32_16x16x32_bf16 v[64:67], v[150:153], v[182:185], v[64:67]
	v_mfma_f32_16x16x32_bf16 v[56:59], v[158:161], v[182:185], v[56:59]
	v_mfma_f32_16x16x32_bf16 v[48:51], v[150:153], v[190:193], v[48:51]
	v_mfma_f32_16x16x32_bf16 v[40:43], v[158:161], v[190:193], v[40:43]
	v_mfma_f32_16x16x32_bf16 v[32:35], v[150:153], v[202:205], v[32:35]
	v_mfma_f32_16x16x32_bf16 v[24:27], v[158:161], v[202:205], v[24:27]
	v_mfma_f32_16x16x32_bf16 v[16:19], v[150:153], v[210:213], v[16:19]
	v_mfma_f32_16x16x32_bf16 v[8:11], v[158:161], v[210:213], v[8:11]
	v_mfma_f32_16x16x32_bf16 v[60:63], v[162:165], v[178:181], v[60:63]
	v_mfma_f32_16x16x32_bf16 v[52:55], v[170:173], v[178:181], v[52:55]
	v_mfma_f32_16x16x32_bf16 v[44:47], v[162:165], v[186:189], v[44:47]
	v_mfma_f32_16x16x32_bf16 v[36:39], v[170:173], v[186:189], v[36:39]
	v_mfma_f32_16x16x32_bf16 v[28:31], v[162:165], v[194:197], v[28:31]
	v_mfma_f32_16x16x32_bf16 v[20:23], v[170:173], v[194:197], v[20:23]
	v_mfma_f32_16x16x32_bf16 v[12:15], v[162:165], v[206:209], v[12:15]
	v_mfma_f32_16x16x32_bf16 v[4:7], v[170:173], v[206:209], v[4:7]
	v_mfma_f32_16x16x32_bf16 v[60:63], v[166:169], v[182:185], v[60:63]
	v_mfma_f32_16x16x32_bf16 v[52:55], v[174:177], v[182:185], v[52:55]
	v_mfma_f32_16x16x32_bf16 v[44:47], v[166:169], v[190:193], v[44:47]
	v_mfma_f32_16x16x32_bf16 v[36:39], v[174:177], v[190:193], v[36:39]
	v_mfma_f32_16x16x32_bf16 v[28:31], v[166:169], v[202:205], v[28:31]
	v_mfma_f32_16x16x32_bf16 v[20:23], v[174:177], v[202:205], v[20:23]
	v_mfma_f32_16x16x32_bf16 v[12:15], v[166:169], v[210:213], v[12:15]
	v_mfma_f32_16x16x32_bf16 v[4:7], v[174:177], v[210:213], v[4:7]
	s_barrier
	s_add_i32 s26, s26, 2
	s_add_u32 s8, s8, 0x100
	s_addc_u32 s9, s9, 0
	s_cmp_gt_u32 s26, 13
	s_cbranch_scc0 .LBB0_1605
	s_setprio 0
	s_cmpk_lt_u32 s14, 0x100
	s_cbranch_scc0 .LBB0_1608
	s_barrier

.LBB0_1681:
	s_add_u32 s72, s40, 0x100
	s_addc_u32 s73, s41, 0
	s_add_u32 s40, s36, 0xb0080
	s_addc_u32 s41, s37, 0
	v_lshl_add_u64 v[130:131], s[40:41], 0, v[126:127]
	v_lshl_add_u64 v[140:141], s[40:41], 0, v[128:129]
	s_mov_b32 s74, -2
	s_mov_b64 s[40:41], 0
	s_mov_b64 s[82:83], 0x80
	v_readfirstlane_b32 s100, v0
	s_cmp_lt_u32 s100, 0x100
	s_cbranch_scc1 .Lgprio_1
	s_setprio 1
.Lgprio_1:
.LBB0_1682:
	s_add_u32 s42, s36, s40
	s_addc_u32 s43, s37, s41
	s_add_u32 s42, s42, 0x100
	s_addc_u32 s43, s43, 0
	s_add_u32 s75, s72, s40
	s_addc_u32 s76, s73, s41
	s_add_i32 s77, 0, 0x10000
	s_cmpk_eq_i32 s40, 0x1500
	s_cselect_b32 s45, s1, s43
	s_cselect_b32 s44, s0, s42
	s_cselect_b32 s43, s39, s76
	s_cselect_b32 s42, s38, s75
	s_add_i32 s75, 0, 0x14000
	v_add_u32_e32 v158, s77, v142
	v_add_u32_e32 v166, s75, v142
	ds_read_b128 v[144:147], v158
	ds_read_b128 v[148:151], v158 offset:1024
	ds_read_b128 v[152:155], v158 offset:2048
	ds_read_b128 v[158:161], v158 offset:3072
	ds_read_b128 v[162:165], v166
	ds_read_b128 v[172:175], v166 offset:1024
	ds_read_b128 v[176:179], v166 offset:2048
	ds_read_b128 v[180:183], v166 offset:3072
	v_lshl_add_u64 v[166:167], v[130:131], 0, s[40:41]
	s_add_i32 m0, s58, 0xc000
	ds_read_b128 v[184:187], v143
	ds_read_b128 v[188:191], v143 offset:1024
	ds_read_b128 v[192:195], v143 offset:2048
	ds_read_b128 v[196:199], v143 offset:3072
	ds_read_b128 v[202:205], v143 offset:4096
	ds_read_b128 v[206:209], v143 offset:5120
	ds_read_b128 v[210:213], v143 offset:6144
	ds_read_b128 v[214:217], v143 offset:7168
	global_load_lds_dwordx4 v[166:167], off
	v_lshl_add_u64 v[166:167], v[140:141], 0, s[40:41]
	s_add_i32 m0, s58, 0xe000
	s_nop 0
	global_load_lds_dwordx4 v[166:167], off
	s_waitcnt vmcnt(8)
	s_waitcnt lgkmcnt(0)
	s_barrier
	s_waitcnt lgkmcnt(0)
	v_mfma_f32_16x16x32_bf16 v[120:123], v[144:147], v[184:187], v[120:123]
	v_mfma_f32_16x16x32_bf16 v[116:119], v[152:155], v[184:187], v[116:119]
	v_mfma_f32_16x16x32_bf16 v[112:115], v[144:147], v[192:195], v[112:115]
	v_mfma_f32_16x16x32_bf16 v[108:111], v[152:155], v[192:195], v[108:111]
	v_mfma_f32_16x16x32_bf16 v[80:83], v[144:147], v[202:205], v[80:83]
	v_mfma_f32_16x16x32_bf16 v[64:67], v[152:155], v[202:205], v[64:67]
	v_mfma_f32_16x16x32_bf16 v[100:103], v[144:147], v[210:213], v[100:103]
	v_mfma_f32_16x16x32_bf16 v[88:91], v[152:155], v[210:213], v[88:91]
	v_mfma_f32_16x16x32_bf16 v[120:123], v[148:151], v[188:191], v[120:123]
	v_mfma_f32_16x16x32_bf16 v[116:119], v[158:161], v[188:191], v[116:119]
	v_mfma_f32_16x16x32_bf16 v[112:115], v[148:151], v[196:199], v[112:115]
	v_mfma_f32_16x16x32_bf16 v[108:111], v[158:161], v[196:199], v[108:111]
	v_mfma_f32_16x16x32_bf16 v[80:83], v[148:151], v[206:209], v[80:83]
	v_mfma_f32_16x16x32_bf16 v[64:67], v[158:161], v[206:209], v[64:67]
	v_mfma_f32_16x16x32_bf16 v[100:103], v[148:151], v[214:217], v[100:103]
	v_mfma_f32_16x16x32_bf16 v[88:91], v[158:161], v[214:217], v[88:91]
	v_mfma_f32_16x16x32_bf16 v[104:107], v[162:165], v[184:187], v[104:107]
	v_mfma_f32_16x16x32_bf16 v[92:95], v[176:179], v[184:187], v[92:95]
	v_mfma_f32_16x16x32_bf16 v[72:75], v[162:165], v[192:195], v[72:75]
	v_mfma_f32_16x16x32_bf16 v[16:19], v[176:179], v[192:195], v[16:19]
	v_mfma_f32_16x16x32_bf16 v[52:55], v[162:165], v[202:205], v[52:55]
	v_mfma_f32_16x16x32_bf16 v[40:43], v[176:179], v[202:205], v[40:43]
	v_mfma_f32_16x16x32_bf16 v[28:31], v[162:165], v[210:213], v[28:31]
	v_mfma_f32_16x16x32_bf16 v[12:15], v[176:179], v[210:213], v[12:15]
	v_mfma_f32_16x16x32_bf16 v[104:107], v[172:175], v[188:191], v[104:107]
	v_mfma_f32_16x16x32_bf16 v[92:95], v[180:183], v[188:191], v[92:95]
	v_mfma_f32_16x16x32_bf16 v[72:75], v[172:175], v[196:199], v[72:75]
	v_mfma_f32_16x16x32_bf16 v[16:19], v[180:183], v[196:199], v[16:19]
	v_mfma_f32_16x16x32_bf16 v[52:55], v[172:175], v[206:209], v[52:55]
	v_mfma_f32_16x16x32_bf16 v[40:43], v[180:183], v[206:209], v[40:43]
	v_mfma_f32_16x16x32_bf16 v[28:31], v[172:175], v[214:217], v[28:31]
	v_mfma_f32_16x16x32_bf16 v[12:15], v[180:183], v[214:217], v[12:15]
	s_barrier
	s_add_i32 s76, s77, s55
	v_lshl_add_u64 v[166:167], s[42:43], 0, v[2:3]
	s_mov_b32 m0, s76
	ds_read_b128 v[184:187], v143 offset:16384
	ds_read_b128 v[188:191], v143 offset:17408
	ds_read_b128 v[192:195], v143 offset:18432
	ds_read_b128 v[196:199], v143 offset:19456
	ds_read_b128 v[202:205], v143 offset:20480
	ds_read_b128 v[206:209], v143 offset:21504
	ds_read_b128 v[210:213], v143 offset:22528
	ds_read_b128 v[214:217], v143 offset:23552
	global_load_lds_dwordx4 v[166:167], off
	s_add_i32 m0, s76, 0x2000
	s_add_u32 s76, s42, 0xb0000
	v_lshl_add_u64 v[218:219], s[42:43], 0, v[124:125]
	s_addc_u32 s77, s43, 0
	s_add_i32 s75, s75, s55
	global_load_lds_dwordx4 v[218:219], off
	v_lshl_add_u64 v[220:221], s[76:77], 0, v[2:3]
	s_mov_b32 m0, s75
	v_lshl_add_u64 v[222:223], s[44:45], 0, v[124:125]
	global_load_lds_dwordx4 v[220:221], off
	v_lshl_add_u64 v[220:221], s[76:77], 0, v[124:125]
	s_add_i32 m0, s75, 0x2000
	s_nop 0
	global_load_lds_dwordx4 v[220:221], off
	v_lshl_add_u64 v[220:221], s[44:45], 0, v[2:3]
	s_mov_b32 m0, s58
	s_nop 0
	global_load_lds_dwordx4 v[220:221], off
	s_mov_b32 m0, s60
	s_nop 0
	global_load_lds_dwordx4 v[222:223], off
	s_waitcnt vmcnt(8)
	s_waitcnt lgkmcnt(0)
	s_barrier
	s_waitcnt lgkmcnt(0)
	v_mfma_f32_16x16x32_bf16 v[76:79], v[144:147], v[184:187], v[76:79]
	v_mfma_f32_16x16x32_bf16 v[60:63], v[152:155], v[184:187], v[60:63]
	v_mfma_f32_16x16x32_bf16 v[96:99], v[144:147], v[192:195], v[96:99]
	v_mfma_f32_16x16x32_bf16 v[84:87], v[152:155], v[192:195], v[84:87]
	v_mfma_f32_16x16x32_bf16 v[68:71], v[144:147], v[202:205], v[68:71]
	v_mfma_f32_16x16x32_bf16 v[56:59], v[152:155], v[202:205], v[56:59]
	v_mfma_f32_16x16x32_bf16 v[136:139], v[144:147], v[210:213], v[136:139]
	v_mfma_f32_16x16x32_bf16 v[132:135], v[152:155], v[210:213], v[132:135]
	v_mfma_f32_16x16x32_bf16 v[76:79], v[148:151], v[188:191], v[76:79]
	v_mfma_f32_16x16x32_bf16 v[60:63], v[158:161], v[188:191], v[60:63]
	v_mfma_f32_16x16x32_bf16 v[96:99], v[148:151], v[196:199], v[96:99]
	v_mfma_f32_16x16x32_bf16 v[84:87], v[158:161], v[196:199], v[84:87]
	v_mfma_f32_16x16x32_bf16 v[68:71], v[148:151], v[206:209], v[68:71]
	v_mfma_f32_16x16x32_bf16 v[56:59], v[158:161], v[206:209], v[56:59]
	v_mfma_f32_16x16x32_bf16 v[136:139], v[148:151], v[214:217], v[136:139]
	v_mfma_f32_16x16x32_bf16 v[132:135], v[158:161], v[214:217], v[132:135]
	v_mfma_f32_16x16x32_bf16 v[48:51], v[162:165], v[184:187], v[48:51]
	v_mfma_f32_16x16x32_bf16 v[36:39], v[176:179], v[184:187], v[36:39]
	v_mfma_f32_16x16x32_bf16 v[24:27], v[162:165], v[192:195], v[24:27]
	v_mfma_f32_16x16x32_bf16 v[8:11], v[176:179], v[192:195], v[8:11]
	v_mfma_f32_16x16x32_bf16 v[44:47], v[162:165], v[202:205], v[44:47]
	v_mfma_f32_16x16x32_bf16 v[32:35], v[176:179], v[202:205], v[32:35]
	v_mfma_f32_16x16x32_bf16 v[20:23], v[162:165], v[210:213], v[20:23]
	v_mfma_f32_16x16x32_bf16 v[4:7], v[176:179], v[210:213], v[4:7]
	v_mfma_f32_16x16x32_bf16 v[48:51], v[172:175], v[188:191], v[48:51]
	v_mfma_f32_16x16x32_bf16 v[36:39], v[180:183], v[188:191], v[36:39]
	v_mfma_f32_16x16x32_bf16 v[24:27], v[172:175], v[196:199], v[24:27]
	v_mfma_f32_16x16x32_bf16 v[8:11], v[180:183], v[196:199], v[8:11]
	v_mfma_f32_16x16x32_bf16 v[44:47], v[172:175], v[206:209], v[44:47]
	v_mfma_f32_16x16x32_bf16 v[32:35], v[180:183], v[206:209], v[32:35]
	v_mfma_f32_16x16x32_bf16 v[20:23], v[172:175], v[214:217], v[20:23]
	v_mfma_f32_16x16x32_bf16 v[4:7], v[180:183], v[214:217], v[4:7]
	s_barrier
	s_add_i32 s75, 0, 0x18000
	s_add_i32 s76, 0, 0x1c000
	v_add_u32_e32 v158, s75, v142
	v_add_u32_e32 v171, s76, v142
	ds_read_b128 v[144:147], v158
	ds_read_b128 v[148:151], v158 offset:1024
	ds_read_b128 v[152:155], v158 offset:2048
	ds_read_b128 v[158:161], v158 offset:3072
	ds_read_b128 v[162:165], v171
	ds_read_b128 v[172:175], v171 offset:1024
	ds_read_b128 v[176:179], v171 offset:2048
	ds_read_b128 v[180:183], v171 offset:3072
	s_add_u32 s44, s44, 0xb0000
	s_addc_u32 s45, s45, 0
	s_mov_b32 m0, s61
	v_lshl_add_u64 v[224:225], s[44:45], 0, v[2:3]
	ds_read_b128 v[184:187], v143 offset:32768
	ds_read_b128 v[188:191], v143 offset:33792
	ds_read_b128 v[192:195], v143 offset:34816
	ds_read_b128 v[196:199], v143 offset:35840
	ds_read_b128 v[202:205], v143 offset:36864
	ds_read_b128 v[206:209], v143 offset:37888
	ds_read_b128 v[210:213], v143 offset:38912
	ds_read_b128 v[214:217], v143 offset:39936
	global_load_lds_dwordx4 v[224:225], off
	v_lshl_add_u64 v[224:225], s[44:45], 0, v[124:125]
	s_mov_b32 m0, s62
	s_nop 0
	global_load_lds_dwordx4 v[224:225], off
	s_waitcnt vmcnt(8)
	s_waitcnt lgkmcnt(0)
	s_barrier
	s_waitcnt lgkmcnt(0)
	v_mfma_f32_16x16x32_bf16 v[120:123], v[144:147], v[184:187], v[120:123]
	v_mfma_f32_16x16x32_bf16 v[116:119], v[152:155], v[184:187], v[116:119]
	v_mfma_f32_16x16x32_bf16 v[112:115], v[144:147], v[192:195], v[112:115]
	v_mfma_f32_16x16x32_bf16 v[108:111], v[152:155], v[192:195], v[108:111]
	v_mfma_f32_16x16x32_bf16 v[80:83], v[144:147], v[202:205], v[80:83]
	v_mfma_f32_16x16x32_bf16 v[64:67], v[152:155], v[202:205], v[64:67]
	v_mfma_f32_16x16x32_bf16 v[100:103], v[144:147], v[210:213], v[100:103]
	v_mfma_f32_16x16x32_bf16 v[88:91], v[152:155], v[210:213], v[88:91]
	v_mfma_f32_16x16x32_bf16 v[120:123], v[148:151], v[188:191], v[120:123]
	v_mfma_f32_16x16x32_bf16 v[116:119], v[158:161], v[188:191], v[116:119]
	v_mfma_f32_16x16x32_bf16 v[112:115], v[148:151], v[196:199], v[112:115]
	v_mfma_f32_16x16x32_bf16 v[108:111], v[158:161], v[196:199], v[108:111]
	v_mfma_f32_16x16x32_bf16 v[80:83], v[148:151], v[206:209], v[80:83]
	v_mfma_f32_16x16x32_bf16 v[64:67], v[158:161], v[206:209], v[64:67]
	v_mfma_f32_16x16x32_bf16 v[100:103], v[148:151], v[214:217], v[100:103]
	v_mfma_f32_16x16x32_bf16 v[88:91], v[158:161], v[214:217], v[88:91]
	v_mfma_f32_16x16x32_bf16 v[104:107], v[162:165], v[184:187], v[104:107]
	v_mfma_f32_16x16x32_bf16 v[92:95], v[176:179], v[184:187], v[92:95]
	v_mfma_f32_16x16x32_bf16 v[72:75], v[162:165], v[192:195], v[72:75]
	v_mfma_f32_16x16x32_bf16 v[16:19], v[176:179], v[192:195], v[16:19]
	v_mfma_f32_16x16x32_bf16 v[52:55], v[162:165], v[202:205], v[52:55]
	v_mfma_f32_16x16x32_bf16 v[40:43], v[176:179], v[202:205], v[40:43]
	v_mfma_f32_16x16x32_bf16 v[28:31], v[162:165], v[210:213], v[28:31]
	v_mfma_f32_16x16x32_bf16 v[12:15], v[176:179], v[210:213], v[12:15]
	v_mfma_f32_16x16x32_bf16 v[104:107], v[172:175], v[188:191], v[104:107]
	v_mfma_f32_16x16x32_bf16 v[92:95], v[180:183], v[188:191], v[92:95]
	v_mfma_f32_16x16x32_bf16 v[72:75], v[172:175], v[196:199], v[72:75]
	v_mfma_f32_16x16x32_bf16 v[16:19], v[180:183], v[196:199], v[16:19]
	v_mfma_f32_16x16x32_bf16 v[52:55], v[172:175], v[206:209], v[52:55]
	v_mfma_f32_16x16x32_bf16 v[40:43], v[180:183], v[206:209], v[40:43]
	v_mfma_f32_16x16x32_bf16 v[28:31], v[172:175], v[214:217], v[28:31]
	v_mfma_f32_16x16x32_bf16 v[12:15], v[180:183], v[214:217], v[12:15]
	s_barrier
	s_add_i32 s44, s75, s55
	v_lshl_add_u64 v[166:167], v[166:167], 0, s[82:83]
	s_mov_b32 m0, s44
	ds_read_b128 v[184:187], v143 offset:49152
	ds_read_b128 v[188:191], v143 offset:50176
	ds_read_b128 v[192:195], v143 offset:51200
	ds_read_b128 v[196:199], v143 offset:52224
	ds_read_b128 v[202:205], v143 offset:53248
	ds_read_b128 v[206:209], v143 offset:54272
	ds_read_b128 v[210:213], v143 offset:55296
	ds_read_b128 v[214:217], v143 offset:56320
	global_load_lds_dwordx4 v[166:167], off
	s_add_i32 m0, s44, 0x2000
	s_add_u32 s42, s42, 0xb0080
	v_lshl_add_u64 v[166:167], v[218:219], 0, s[82:83]
	s_addc_u32 s43, s43, 0
	s_add_i32 s44, s76, s55
	global_load_lds_dwordx4 v[166:167], off
	v_lshl_add_u64 v[166:167], s[42:43], 0, v[2:3]
	s_mov_b32 m0, s44
	s_nop 0
	global_load_lds_dwordx4 v[166:167], off
	v_lshl_add_u64 v[166:167], s[42:43], 0, v[124:125]
	s_add_i32 m0, s44, 0x2000
	s_nop 0
	global_load_lds_dwordx4 v[166:167], off
	v_lshl_add_u64 v[166:167], v[220:221], 0, s[82:83]
	s_mov_b32 m0, s63
	s_nop 0
	global_load_lds_dwordx4 v[166:167], off
	v_lshl_add_u64 v[166:167], v[222:223], 0, s[82:83]
	s_mov_b32 m0, s66
	s_nop 0
	global_load_lds_dwordx4 v[166:167], off
	s_waitcnt vmcnt(8)
	s_waitcnt lgkmcnt(0)
	s_barrier
	s_waitcnt lgkmcnt(0)
	v_mfma_f32_16x16x32_bf16 v[76:79], v[144:147], v[184:187], v[76:79]
	v_mfma_f32_16x16x32_bf16 v[60:63], v[152:155], v[184:187], v[60:63]
	v_mfma_f32_16x16x32_bf16 v[96:99], v[144:147], v[192:195], v[96:99]
	v_mfma_f32_16x16x32_bf16 v[84:87], v[152:155], v[192:195], v[84:87]
	v_mfma_f32_16x16x32_bf16 v[68:71], v[144:147], v[202:205], v[68:71]
	v_mfma_f32_16x16x32_bf16 v[56:59], v[152:155], v[202:205], v[56:59]
	v_mfma_f32_16x16x32_bf16 v[136:139], v[144:147], v[210:213], v[136:139]
	v_mfma_f32_16x16x32_bf16 v[132:135], v[152:155], v[210:213], v[132:135]
	v_mfma_f32_16x16x32_bf16 v[76:79], v[148:151], v[188:191], v[76:79]
	v_mfma_f32_16x16x32_bf16 v[60:63], v[158:161], v[188:191], v[60:63]
	v_mfma_f32_16x16x32_bf16 v[96:99], v[148:151], v[196:199], v[96:99]
	v_mfma_f32_16x16x32_bf16 v[84:87], v[158:161], v[196:199], v[84:87]
	v_mfma_f32_16x16x32_bf16 v[68:71], v[148:151], v[206:209], v[68:71]
	v_mfma_f32_16x16x32_bf16 v[56:59], v[158:161], v[206:209], v[56:59]
	v_mfma_f32_16x16x32_bf16 v[136:139], v[148:151], v[214:217], v[136:139]
	v_mfma_f32_16x16x32_bf16 v[132:135], v[158:161], v[214:217], v[132:135]
	v_mfma_f32_16x16x32_bf16 v[48:51], v[162:165], v[184:187], v[48:51]
	v_mfma_f32_16x16x32_bf16 v[36:39], v[176:179], v[184:187], v[36:39]
	v_mfma_f32_16x16x32_bf16 v[24:27], v[162:165], v[192:195], v[24:27]
	v_mfma_f32_16x16x32_bf16 v[8:11], v[176:179], v[192:195], v[8:11]
	v_mfma_f32_16x16x32_bf16 v[44:47], v[162:165], v[202:205], v[44:47]
	v_mfma_f32_16x16x32_bf16 v[32:35], v[176:179], v[202:205], v[32:35]
	v_mfma_f32_16x16x32_bf16 v[20:23], v[162:165], v[210:213], v[20:23]
	v_mfma_f32_16x16x32_bf16 v[4:7], v[176:179], v[210:213], v[4:7]
	v_mfma_f32_16x16x32_bf16 v[48:51], v[172:175], v[188:191], v[48:51]
	v_mfma_f32_16x16x32_bf16 v[36:39], v[180:183], v[188:191], v[36:39]
	v_mfma_f32_16x16x32_bf16 v[24:27], v[172:175], v[196:199], v[24:27]
	v_mfma_f32_16x16x32_bf16 v[8:11], v[180:183], v[196:199], v[8:11]
	v_mfma_f32_16x16x32_bf16 v[44:47], v[172:175], v[206:209], v[44:47]
	v_mfma_f32_16x16x32_bf16 v[32:35], v[180:183], v[206:209], v[32:35]
	v_mfma_f32_16x16x32_bf16 v[20:23], v[172:175], v[214:217], v[20:23]
	v_mfma_f32_16x16x32_bf16 v[4:7], v[180:183], v[214:217], v[4:7]
	s_barrier
	s_add_i32 s74, s74, 2
	s_add_u32 s40, s40, 0x100
	s_addc_u32 s41, s41, 0
	s_cmp_gt_u32 s74, 41
	s_cbranch_scc0 .LBB0_1682
	s_setprio 0
	s_and_b64 vcc, exec, s[34:35]
	s_mov_b64 s[82:83], 0x9400200
	s_mov_b64 s[74:75], 0x9400280
	s_cbranch_vccz .LBB0_1685
	s_barrier

.LBB0_1861:
	s_add_u32 s51, s24, 0x100
	v_mov_b32_e32 v4, 0
	s_addc_u32 s52, s25, 0
	s_mov_b32 s53, -2
	v_mov_b32_e32 v5, v4
	v_mov_b32_e32 v6, v4
	v_mov_b32_e32 v7, v4
	v_mov_b32_e32 v8, v4
	v_mov_b32_e32 v9, v4
	v_mov_b32_e32 v10, v4
	v_mov_b32_e32 v11, v4
	v_mov_b32_e32 v20, v4
	v_mov_b32_e32 v21, v4
	v_mov_b32_e32 v22, v4
	v_mov_b32_e32 v23, v4
	v_mov_b32_e32 v24, v4
	v_mov_b32_e32 v25, v4
	v_mov_b32_e32 v26, v4
	v_mov_b32_e32 v27, v4
	v_mov_b32_e32 v36, v4
	v_mov_b32_e32 v37, v4
	v_mov_b32_e32 v38, v4
	v_mov_b32_e32 v39, v4
	v_mov_b32_e32 v40, v4
	v_mov_b32_e32 v41, v4
	v_mov_b32_e32 v42, v4
	v_mov_b32_e32 v43, v4
	v_mov_b32_e32 v52, v4
	v_mov_b32_e32 v53, v4
	v_mov_b32_e32 v54, v4
	v_mov_b32_e32 v55, v4
	v_mov_b32_e32 v56, v4
	v_mov_b32_e32 v57, v4
	v_mov_b32_e32 v58, v4
	v_mov_b32_e32 v59, v4
	v_mov_b32_e32 v12, v4
	v_mov_b32_e32 v13, v4
	v_mov_b32_e32 v14, v4
	v_mov_b32_e32 v15, v4
	v_mov_b32_e32 v16, v4
	v_mov_b32_e32 v17, v4
	v_mov_b32_e32 v18, v4
	v_mov_b32_e32 v19, v4
	v_mov_b32_e32 v28, v4
	v_mov_b32_e32 v29, v4
	v_mov_b32_e32 v30, v4
	v_mov_b32_e32 v31, v4
	v_mov_b32_e32 v32, v4
	v_mov_b32_e32 v33, v4
	v_mov_b32_e32 v34, v4
	v_mov_b32_e32 v35, v4
	v_mov_b32_e32 v44, v4
	v_mov_b32_e32 v45, v4
	v_mov_b32_e32 v46, v4
	v_mov_b32_e32 v47, v4
	v_mov_b32_e32 v48, v4
	v_mov_b32_e32 v49, v4
	v_mov_b32_e32 v50, v4
	v_mov_b32_e32 v51, v4
	v_mov_b32_e32 v60, v4
	v_mov_b32_e32 v61, v4
	v_mov_b32_e32 v62, v4
	v_mov_b32_e32 v63, v4
	v_mov_b32_e32 v64, v4
	v_mov_b32_e32 v65, v4
	v_mov_b32_e32 v66, v4
	v_mov_b32_e32 v67, v4
	v_mov_b32_e32 v68, v4
	v_mov_b32_e32 v69, v4
	v_mov_b32_e32 v70, v4
	v_mov_b32_e32 v71, v4
	v_mov_b32_e32 v72, v4
	v_mov_b32_e32 v73, v4
	v_mov_b32_e32 v74, v4
	v_mov_b32_e32 v75, v4
	v_mov_b32_e32 v84, v4
	v_mov_b32_e32 v85, v4
	v_mov_b32_e32 v86, v4
	v_mov_b32_e32 v87, v4
	v_mov_b32_e32 v88, v4
	v_mov_b32_e32 v89, v4
	v_mov_b32_e32 v90, v4
	v_mov_b32_e32 v91, v4
	v_mov_b32_e32 v100, v4
	v_mov_b32_e32 v101, v4
	v_mov_b32_e32 v102, v4
	v_mov_b32_e32 v103, v4
	v_mov_b32_e32 v104, v4
	v_mov_b32_e32 v105, v4
	v_mov_b32_e32 v106, v4
	v_mov_b32_e32 v107, v4
	v_mov_b32_e32 v116, v4
	v_mov_b32_e32 v117, v4
	v_mov_b32_e32 v118, v4
	v_mov_b32_e32 v119, v4
	v_mov_b32_e32 v120, v4
	v_mov_b32_e32 v121, v4
	v_mov_b32_e32 v122, v4
	v_mov_b32_e32 v123, v4
	v_mov_b32_e32 v76, v4
	v_mov_b32_e32 v77, v4
	v_mov_b32_e32 v78, v4
	v_mov_b32_e32 v79, v4
	v_mov_b32_e32 v80, v4
	v_mov_b32_e32 v81, v4
	v_mov_b32_e32 v82, v4
	v_mov_b32_e32 v83, v4
	v_mov_b32_e32 v92, v4
	v_mov_b32_e32 v93, v4
	v_mov_b32_e32 v94, v4
	v_mov_b32_e32 v95, v4
	v_mov_b32_e32 v96, v4
	v_mov_b32_e32 v97, v4
	v_mov_b32_e32 v98, v4
	v_mov_b32_e32 v99, v4
	v_mov_b32_e32 v108, v4
	v_mov_b32_e32 v109, v4
	v_mov_b32_e32 v110, v4
	v_mov_b32_e32 v111, v4
	v_mov_b32_e32 v112, v4
	v_mov_b32_e32 v113, v4
	v_mov_b32_e32 v114, v4
	v_mov_b32_e32 v115, v4
	v_mov_b32_e32 v124, v4
	v_mov_b32_e32 v125, v4
	v_mov_b32_e32 v126, v4
	v_mov_b32_e32 v127, v4
	v_mov_b32_e32 v128, v4
	v_mov_b32_e32 v129, v4
	v_mov_b32_e32 v130, v4
	v_mov_b32_e32 v131, v4
	s_mov_b64 s[56:57], 0x80
	v_readfirstlane_b32 s100, v0
	s_cmp_lt_u32 s100, 0x100
	s_cbranch_scc1 .Lgprio_0
	s_setprio 1
.Lgprio_0:
.LBB0_1862:
	s_add_u32 s0, s22, 0x100
	s_addc_u32 s1, s23, 0
	s_add_i32 s54, 0, 0x10000
	s_cmp_eq_u32 s53, 40
	s_cselect_b32 s27, s19, s1
	s_cselect_b32 s26, s18, s0
	v_add_u32_e32 v2, s54, v155
	s_cselect_b32 s25, s21, s52
	s_cselect_b32 s24, s20, s51
	s_add_i32 s55, 0, 0x14000
	ds_read_b128 v[146:149], v2
	ds_read_b128 v[150:153], v2 offset:1024
	ds_read_b128 v[158:161], v2 offset:2048
	ds_read_b128 v[162:165], v2 offset:3072
	v_add_u32_e32 v2, s55, v155
	ds_read_b128 v[166:169], v2
	ds_read_b128 v[170:173], v2 offset:1024
	ds_read_b128 v[174:177], v2 offset:2048
	ds_read_b128 v[178:181], v2 offset:3072
	v_lshl_add_u64 v[198:199], s[22:23], 0, v[142:143]
	s_add_i32 m0, s36, 0xc000
	ds_read_b128 v[182:185], v157
	ds_read_b128 v[186:189], v157 offset:1024
	ds_read_b128 v[190:193], v157 offset:2048
	ds_read_b128 v[194:197], v157 offset:3072
	ds_read_b128 v[202:205], v157 offset:4096
	ds_read_b128 v[206:209], v157 offset:5120
	ds_read_b128 v[210:213], v157 offset:6144
	ds_read_b128 v[214:217], v157 offset:7168
	global_load_lds_dwordx4 v[198:199], off
	v_lshl_add_u64 v[198:199], s[22:23], 0, v[144:145]
	s_add_i32 m0, s36, 0xe000
	s_nop 0
	global_load_lds_dwordx4 v[198:199], off
	s_waitcnt vmcnt(8)
	s_waitcnt lgkmcnt(0)
	s_barrier
	s_waitcnt lgkmcnt(0)
	v_mfma_f32_16x16x32_bf16 v[128:131], v[146:149], v[182:185], v[128:131]
	v_mfma_f32_16x16x32_bf16 v[124:127], v[158:161], v[182:185], v[124:127]
	v_mfma_f32_16x16x32_bf16 v[112:115], v[146:149], v[190:193], v[112:115]
	v_mfma_f32_16x16x32_bf16 v[108:111], v[158:161], v[190:193], v[108:111]
	v_mfma_f32_16x16x32_bf16 v[96:99], v[146:149], v[202:205], v[96:99]
	v_mfma_f32_16x16x32_bf16 v[92:95], v[158:161], v[202:205], v[92:95]
	v_mfma_f32_16x16x32_bf16 v[80:83], v[146:149], v[210:213], v[80:83]
	v_mfma_f32_16x16x32_bf16 v[76:79], v[158:161], v[210:213], v[76:79]
	v_mfma_f32_16x16x32_bf16 v[128:131], v[150:153], v[186:189], v[128:131]
	v_mfma_f32_16x16x32_bf16 v[124:127], v[162:165], v[186:189], v[124:127]
	v_mfma_f32_16x16x32_bf16 v[112:115], v[150:153], v[194:197], v[112:115]
	v_mfma_f32_16x16x32_bf16 v[108:111], v[162:165], v[194:197], v[108:111]
	v_mfma_f32_16x16x32_bf16 v[96:99], v[150:153], v[206:209], v[96:99]
	v_mfma_f32_16x16x32_bf16 v[92:95], v[162:165], v[206:209], v[92:95]
	v_mfma_f32_16x16x32_bf16 v[80:83], v[150:153], v[214:217], v[80:83]
	v_mfma_f32_16x16x32_bf16 v[76:79], v[162:165], v[214:217], v[76:79]
	v_mfma_f32_16x16x32_bf16 v[120:123], v[166:169], v[182:185], v[120:123]
	v_mfma_f32_16x16x32_bf16 v[116:119], v[174:177], v[182:185], v[116:119]
	v_mfma_f32_16x16x32_bf16 v[104:107], v[166:169], v[190:193], v[104:107]
	v_mfma_f32_16x16x32_bf16 v[100:103], v[174:177], v[190:193], v[100:103]
	v_mfma_f32_16x16x32_bf16 v[88:91], v[166:169], v[202:205], v[88:91]
	v_mfma_f32_16x16x32_bf16 v[84:87], v[174:177], v[202:205], v[84:87]
	v_mfma_f32_16x16x32_bf16 v[72:75], v[166:169], v[210:213], v[72:75]
	v_mfma_f32_16x16x32_bf16 v[68:71], v[174:177], v[210:213], v[68:71]
	v_mfma_f32_16x16x32_bf16 v[120:123], v[170:173], v[186:189], v[120:123]
	v_mfma_f32_16x16x32_bf16 v[116:119], v[178:181], v[186:189], v[116:119]
	v_mfma_f32_16x16x32_bf16 v[104:107], v[170:173], v[194:197], v[104:107]
	v_mfma_f32_16x16x32_bf16 v[100:103], v[178:181], v[194:197], v[100:103]
	v_mfma_f32_16x16x32_bf16 v[88:91], v[170:173], v[206:209], v[88:91]
	v_mfma_f32_16x16x32_bf16 v[84:87], v[178:181], v[206:209], v[84:87]
	v_mfma_f32_16x16x32_bf16 v[72:75], v[170:173], v[214:217], v[72:75]
	v_mfma_f32_16x16x32_bf16 v[68:71], v[178:181], v[214:217], v[68:71]
	s_barrier
	s_add_i32 s22, s54, s35
	v_lshl_add_u64 v[198:199], s[24:25], 0, v[136:137]
	s_mov_b32 m0, s22
	ds_read_b128 v[182:185], v157 offset:16384
	ds_read_b128 v[186:189], v157 offset:17408
	ds_read_b128 v[190:193], v157 offset:18432
	ds_read_b128 v[194:197], v157 offset:19456
	ds_read_b128 v[202:205], v157 offset:20480
	ds_read_b128 v[206:209], v157 offset:21504
	ds_read_b128 v[210:213], v157 offset:22528
	ds_read_b128 v[214:217], v157 offset:23552
	global_load_lds_dwordx4 v[198:199], off
	s_add_i32 m0, s22, 0x2000
	s_add_u32 s22, s24, 0xb0000
	v_lshl_add_u64 v[218:219], s[24:25], 0, v[138:139]
	s_addc_u32 s23, s25, 0
	s_add_i32 s54, s55, s35
	global_load_lds_dwordx4 v[218:219], off
	v_lshl_add_u64 v[220:221], s[22:23], 0, v[136:137]
	s_mov_b32 m0, s54
	v_lshl_add_u64 v[222:223], s[26:27], 0, v[138:139]
	global_load_lds_dwordx4 v[220:221], off
	v_lshl_add_u64 v[220:221], s[22:23], 0, v[138:139]
	s_add_i32 m0, s54, 0x2000
	s_nop 0
	global_load_lds_dwordx4 v[220:221], off
	v_lshl_add_u64 v[220:221], s[26:27], 0, v[136:137]
	s_mov_b32 m0, s36
	s_nop 0
	global_load_lds_dwordx4 v[220:221], off
	s_mov_b32 m0, s37
	s_nop 0
	global_load_lds_dwordx4 v[222:223], off
	s_waitcnt vmcnt(8)
	s_waitcnt lgkmcnt(0)
	s_barrier
	s_waitcnt lgkmcnt(0)
	v_mfma_f32_16x16x32_bf16 v[64:67], v[146:149], v[182:185], v[64:67]
	v_mfma_f32_16x16x32_bf16 v[60:63], v[158:161], v[182:185], v[60:63]
	v_mfma_f32_16x16x32_bf16 v[48:51], v[146:149], v[190:193], v[48:51]
	v_mfma_f32_16x16x32_bf16 v[44:47], v[158:161], v[190:193], v[44:47]
	v_mfma_f32_16x16x32_bf16 v[32:35], v[146:149], v[202:205], v[32:35]
	v_mfma_f32_16x16x32_bf16 v[28:31], v[158:161], v[202:205], v[28:31]
	v_mfma_f32_16x16x32_bf16 v[16:19], v[146:149], v[210:213], v[16:19]
	v_mfma_f32_16x16x32_bf16 v[12:15], v[158:161], v[210:213], v[12:15]
	v_mfma_f32_16x16x32_bf16 v[64:67], v[150:153], v[186:189], v[64:67]
	v_mfma_f32_16x16x32_bf16 v[60:63], v[162:165], v[186:189], v[60:63]
	v_mfma_f32_16x16x32_bf16 v[48:51], v[150:153], v[194:197], v[48:51]
	v_mfma_f32_16x16x32_bf16 v[44:47], v[162:165], v[194:197], v[44:47]
	v_mfma_f32_16x16x32_bf16 v[32:35], v[150:153], v[206:209], v[32:35]
	v_mfma_f32_16x16x32_bf16 v[28:31], v[162:165], v[206:209], v[28:31]
	v_mfma_f32_16x16x32_bf16 v[16:19], v[150:153], v[214:217], v[16:19]
	v_mfma_f32_16x16x32_bf16 v[12:15], v[162:165], v[214:217], v[12:15]
	v_mfma_f32_16x16x32_bf16 v[56:59], v[166:169], v[182:185], v[56:59]
	v_mfma_f32_16x16x32_bf16 v[52:55], v[174:177], v[182:185], v[52:55]
	v_mfma_f32_16x16x32_bf16 v[40:43], v[166:169], v[190:193], v[40:43]
	v_mfma_f32_16x16x32_bf16 v[36:39], v[174:177], v[190:193], v[36:39]
	v_mfma_f32_16x16x32_bf16 v[24:27], v[166:169], v[202:205], v[24:27]
	v_mfma_f32_16x16x32_bf16 v[20:23], v[174:177], v[202:205], v[20:23]
	v_mfma_f32_16x16x32_bf16 v[8:11], v[166:169], v[210:213], v[8:11]
	v_mfma_f32_16x16x32_bf16 v[4:7], v[174:177], v[210:213], v[4:7]
	v_mfma_f32_16x16x32_bf16 v[56:59], v[170:173], v[186:189], v[56:59]
	v_mfma_f32_16x16x32_bf16 v[52:55], v[178:181], v[186:189], v[52:55]
	v_mfma_f32_16x16x32_bf16 v[40:43], v[170:173], v[194:197], v[40:43]
	v_mfma_f32_16x16x32_bf16 v[36:39], v[178:181], v[194:197], v[36:39]
	v_mfma_f32_16x16x32_bf16 v[24:27], v[170:173], v[206:209], v[24:27]
	v_mfma_f32_16x16x32_bf16 v[20:23], v[178:181], v[206:209], v[20:23]
	v_mfma_f32_16x16x32_bf16 v[8:11], v[170:173], v[214:217], v[8:11]
	v_mfma_f32_16x16x32_bf16 v[4:7], v[178:181], v[214:217], v[4:7]
	s_barrier
	s_add_i32 s54, 0, 0x18000
	v_add_u32_e32 v2, s54, v155
	s_add_i32 s55, 0, 0x1c000
	ds_read_b128 v[146:149], v2
	ds_read_b128 v[150:153], v2 offset:1024
	ds_read_b128 v[158:161], v2 offset:2048
	ds_read_b128 v[162:165], v2 offset:3072
	v_add_u32_e32 v2, s55, v155
	ds_read_b128 v[166:169], v2
	ds_read_b128 v[170:173], v2 offset:1024
	ds_read_b128 v[174:177], v2 offset:2048
	ds_read_b128 v[178:181], v2 offset:3072
	s_add_u32 s22, s26, 0xb0000
	s_addc_u32 s23, s27, 0
	s_mov_b32 m0, s38
	v_lshl_add_u64 v[224:225], s[22:23], 0, v[136:137]
	ds_read_b128 v[182:185], v157 offset:32768
	ds_read_b128 v[186:189], v157 offset:33792
	ds_read_b128 v[190:193], v157 offset:34816
	ds_read_b128 v[194:197], v157 offset:35840
	ds_read_b128 v[202:205], v157 offset:36864
	ds_read_b128 v[206:209], v157 offset:37888
	ds_read_b128 v[210:213], v157 offset:38912
	ds_read_b128 v[214:217], v157 offset:39936
	global_load_lds_dwordx4 v[224:225], off
	v_lshl_add_u64 v[224:225], s[22:23], 0, v[138:139]
	s_mov_b32 m0, s39
	s_nop 0
	global_load_lds_dwordx4 v[224:225], off
	s_waitcnt vmcnt(8)
	s_waitcnt lgkmcnt(0)
	s_barrier
	s_waitcnt lgkmcnt(0)
	v_mfma_f32_16x16x32_bf16 v[128:131], v[146:149], v[182:185], v[128:131]
	v_mfma_f32_16x16x32_bf16 v[124:127], v[158:161], v[182:185], v[124:127]
	v_mfma_f32_16x16x32_bf16 v[112:115], v[146:149], v[190:193], v[112:115]
	v_mfma_f32_16x16x32_bf16 v[108:111], v[158:161], v[190:193], v[108:111]
	v_mfma_f32_16x16x32_bf16 v[96:99], v[146:149], v[202:205], v[96:99]
	v_mfma_f32_16x16x32_bf16 v[92:95], v[158:161], v[202:205], v[92:95]
	v_mfma_f32_16x16x32_bf16 v[80:83], v[146:149], v[210:213], v[80:83]
	v_mfma_f32_16x16x32_bf16 v[76:79], v[158:161], v[210:213], v[76:79]
	v_mfma_f32_16x16x32_bf16 v[128:131], v[150:153], v[186:189], v[128:131]
	v_mfma_f32_16x16x32_bf16 v[124:127], v[162:165], v[186:189], v[124:127]
	v_mfma_f32_16x16x32_bf16 v[112:115], v[150:153], v[194:197], v[112:115]
	v_mfma_f32_16x16x32_bf16 v[108:111], v[162:165], v[194:197], v[108:111]
	v_mfma_f32_16x16x32_bf16 v[96:99], v[150:153], v[206:209], v[96:99]
	v_mfma_f32_16x16x32_bf16 v[92:95], v[162:165], v[206:209], v[92:95]
	v_mfma_f32_16x16x32_bf16 v[80:83], v[150:153], v[214:217], v[80:83]
	v_mfma_f32_16x16x32_bf16 v[76:79], v[162:165], v[214:217], v[76:79]
	v_mfma_f32_16x16x32_bf16 v[120:123], v[166:169], v[182:185], v[120:123]
	v_mfma_f32_16x16x32_bf16 v[116:119], v[174:177], v[182:185], v[116:119]
	v_mfma_f32_16x16x32_bf16 v[104:107], v[166:169], v[190:193], v[104:107]
	v_mfma_f32_16x16x32_bf16 v[100:103], v[174:177], v[190:193], v[100:103]
	v_mfma_f32_16x16x32_bf16 v[88:91], v[166:169], v[202:205], v[88:91]
	v_mfma_f32_16x16x32_bf16 v[84:87], v[174:177], v[202:205], v[84:87]
	v_mfma_f32_16x16x32_bf16 v[72:75], v[166:169], v[210:213], v[72:75]
	v_mfma_f32_16x16x32_bf16 v[68:71], v[174:177], v[210:213], v[68:71]
	v_mfma_f32_16x16x32_bf16 v[120:123], v[170:173], v[186:189], v[120:123]
	v_mfma_f32_16x16x32_bf16 v[116:119], v[178:181], v[186:189], v[116:119]
	v_mfma_f32_16x16x32_bf16 v[104:107], v[170:173], v[194:197], v[104:107]
	v_mfma_f32_16x16x32_bf16 v[100:103], v[178:181], v[194:197], v[100:103]
	v_mfma_f32_16x16x32_bf16 v[88:91], v[170:173], v[206:209], v[88:91]
	v_mfma_f32_16x16x32_bf16 v[84:87], v[178:181], v[206:209], v[84:87]
	v_mfma_f32_16x16x32_bf16 v[72:75], v[170:173], v[214:217], v[72:75]
	v_mfma_f32_16x16x32_bf16 v[68:71], v[178:181], v[214:217], v[68:71]
	s_barrier
	s_add_i32 s22, s54, s35
	v_lshl_add_u64 v[198:199], v[198:199], 0, s[56:57]
	s_mov_b32 m0, s22
	ds_read_b128 v[182:185], v157 offset:49152
	ds_read_b128 v[186:189], v157 offset:50176
	ds_read_b128 v[190:193], v157 offset:51200
	ds_read_b128 v[194:197], v157 offset:52224
	ds_read_b128 v[202:205], v157 offset:53248
	ds_read_b128 v[206:209], v157 offset:54272
	ds_read_b128 v[210:213], v157 offset:55296
	ds_read_b128 v[214:217], v157 offset:56320
	global_load_lds_dwordx4 v[198:199], off
	s_add_i32 m0, s22, 0x2000
	s_add_u32 s22, s24, 0xb0080
	v_lshl_add_u64 v[198:199], v[218:219], 0, s[56:57]
	s_addc_u32 s23, s25, 0
	s_add_i32 s24, s55, s35
	global_load_lds_dwordx4 v[198:199], off
	v_lshl_add_u64 v[198:199], s[22:23], 0, v[136:137]
	s_mov_b32 m0, s24
	s_nop 0
	global_load_lds_dwordx4 v[198:199], off
	v_lshl_add_u64 v[198:199], s[22:23], 0, v[138:139]
	s_add_i32 m0, s24, 0x2000
	s_nop 0
	global_load_lds_dwordx4 v[198:199], off
	v_lshl_add_u64 v[198:199], v[220:221], 0, s[56:57]
	s_mov_b32 m0, s41
	s_nop 0
	global_load_lds_dwordx4 v[198:199], off
	v_lshl_add_u64 v[198:199], v[222:223], 0, s[56:57]
	s_mov_b32 m0, s42
	s_nop 0
	global_load_lds_dwordx4 v[198:199], off
	s_waitcnt vmcnt(8)
	s_waitcnt lgkmcnt(0)
	s_barrier
	s_waitcnt lgkmcnt(0)
	v_mfma_f32_16x16x32_bf16 v[64:67], v[146:149], v[182:185], v[64:67]
	v_mfma_f32_16x16x32_bf16 v[60:63], v[158:161], v[182:185], v[60:63]
	v_mfma_f32_16x16x32_bf16 v[48:51], v[146:149], v[190:193], v[48:51]
	v_mfma_f32_16x16x32_bf16 v[44:47], v[158:161], v[190:193], v[44:47]
	v_mfma_f32_16x16x32_bf16 v[32:35], v[146:149], v[202:205], v[32:35]
	v_mfma_f32_16x16x32_bf16 v[28:31], v[158:161], v[202:205], v[28:31]
	v_mfma_f32_16x16x32_bf16 v[16:19], v[146:149], v[210:213], v[16:19]
	v_mfma_f32_16x16x32_bf16 v[12:15], v[158:161], v[210:213], v[12:15]
	v_mfma_f32_16x16x32_bf16 v[64:67], v[150:153], v[186:189], v[64:67]
	v_mfma_f32_16x16x32_bf16 v[60:63], v[162:165], v[186:189], v[60:63]
	v_mfma_f32_16x16x32_bf16 v[48:51], v[150:153], v[194:197], v[48:51]
	v_mfma_f32_16x16x32_bf16 v[44:47], v[162:165], v[194:197], v[44:47]
	v_mfma_f32_16x16x32_bf16 v[32:35], v[150:153], v[206:209], v[32:35]
	v_mfma_f32_16x16x32_bf16 v[28:31], v[162:165], v[206:209], v[28:31]
	v_mfma_f32_16x16x32_bf16 v[16:19], v[150:153], v[214:217], v[16:19]
	v_mfma_f32_16x16x32_bf16 v[12:15], v[162:165], v[214:217], v[12:15]
	v_mfma_f32_16x16x32_bf16 v[56:59], v[166:169], v[182:185], v[56:59]
	v_mfma_f32_16x16x32_bf16 v[52:55], v[174:177], v[182:185], v[52:55]
	v_mfma_f32_16x16x32_bf16 v[40:43], v[166:169], v[190:193], v[40:43]
	v_mfma_f32_16x16x32_bf16 v[36:39], v[174:177], v[190:193], v[36:39]
	v_mfma_f32_16x16x32_bf16 v[24:27], v[166:169], v[202:205], v[24:27]
	v_mfma_f32_16x16x32_bf16 v[20:23], v[174:177], v[202:205], v[20:23]
	v_mfma_f32_16x16x32_bf16 v[8:11], v[166:169], v[210:213], v[8:11]
	v_mfma_f32_16x16x32_bf16 v[4:7], v[174:177], v[210:213], v[4:7]
	v_mfma_f32_16x16x32_bf16 v[56:59], v[170:173], v[186:189], v[56:59]
	v_mfma_f32_16x16x32_bf16 v[52:55], v[178:181], v[186:189], v[52:55]
	v_mfma_f32_16x16x32_bf16 v[40:43], v[170:173], v[194:197], v[40:43]
	v_mfma_f32_16x16x32_bf16 v[36:39], v[178:181], v[194:197], v[36:39]
	v_mfma_f32_16x16x32_bf16 v[24:27], v[170:173], v[206:209], v[24:27]
	v_mfma_f32_16x16x32_bf16 v[20:23], v[178:181], v[206:209], v[20:23]
	v_mfma_f32_16x16x32_bf16 v[8:11], v[170:173], v[214:217], v[8:11]
	v_mfma_f32_16x16x32_bf16 v[4:7], v[178:181], v[214:217], v[4:7]
	s_barrier
	s_add_i32 s53, s53, 2
	s_add_u32 s51, s51, 0x100
	s_addc_u32 s52, s52, 0
	s_cmp_gt_u32 s53, 41
	s_mov_b64 s[22:23], s[0:1]
	s_cbranch_scc0 .LBB0_1862
	s_setprio 0
	s_and_b64 vcc, exec, s[16:17]
	s_cbranch_vccz .LBB0_1865
	s_barrier
